# lean barrier + SCAN_C stagger + WIN silu epilogue via v_rcp_f32 (f32) instead of IEEE div expansion + MLP1 relu canonicalize removed
# speedup vs baseline: 1.0148x; 1.0059x over previous
.LBB0_748:
	s_lshl_b32 s14, s34, 8
	s_ashr_i32 s15, s14, 31
	s_lshl_b64 s[14:15], s[14:15], 13
	s_add_u32 s21, s0, s14
	s_addc_u32 s34, s1, s15
	s_lshl_b32 s14, s64, 8
	v_mov_b32_e32 v146, v1
	v_mov_b32_e32 v147, v148
	s_ashr_i32 s15, s14, 31
	s_lshl_b64 s[14:15], s[14:15], 1
	v_add_u32_e32 v146, s30, v146
	v_max_f32_e32 v126, 0, v126
	v_max_f32_e32 v122, 0, v122
	v_max_f32_e32 v127, 0, v127
	v_max_f32_e32 v123, 0, v123
	s_add_u32 s42, s21, s14
	v_lshl_add_u32 v154, v147, 3, s31
	v_ashrrev_i32_e32 v147, 31, v146
	v_pk_mul_f32 v[126:127], v[126:127], v[126:127]
	v_pk_mul_f32 v[122:123], v[122:123], v[122:123]
	v_max_f32_e32 v128, 0, v128
	v_max_f32_e32 v124, 0, v124
	v_max_f32_e32 v129, 0, v129
	v_max_f32_e32 v125, 0, v125
	s_addc_u32 s43, s34, s15
	v_pk_mul_f32 v[128:129], v[128:129], v[128:129]
	v_pk_mul_f32 v[156:157], v[124:125], v[124:125]
	v_cvt_pk_bf16_f32 v124, v126, v127
	v_cvt_pk_bf16_f32 v126, v122, v123
	v_lshlrev_b64 v[122:123], 13, v[146:147]
	v_ashrrev_i32_e32 v155, 31, v154
	v_cvt_pk_bf16_f32 v125, v128, v129
	v_lshl_add_u64 v[128:129], s[42:43], 0, v[122:123]
	v_lshlrev_b64 v[122:123], 1, v[154:155]
	v_cvt_pk_bf16_f32 v127, v156, v157
	v_lshl_add_u64 v[128:129], v[128:129], 0, v[122:123]
	v_max_f32_e32 v114, 0, v114
	v_max_f32_e32 v115, 0, v115
	global_store_dwordx4 v[128:129], v[124:127], off
	s_nop 1
	v_pk_mul_f32 v[124:125], v[114:115], v[114:115]
	v_max_f32_e32 v116, 0, v116
	v_max_f32_e32 v118, 0, v118
	v_max_f32_e32 v119, 0, v119
	v_max_f32_e32 v114, 0, v120
	v_max_f32_e32 v115, 0, v121
	v_max_f32_e32 v117, 0, v117
	v_pk_mul_f32 v[118:119], v[118:119], v[118:119]
	v_pk_mul_f32 v[120:121], v[114:115], v[114:115]
	v_pk_mul_f32 v[126:127], v[116:117], v[116:117]
	v_cvt_pk_bf16_f32 v114, v118, v119
	v_cvt_pk_bf16_f32 v115, v120, v121
	v_cvt_pk_bf16_f32 v116, v124, v125
	v_cvt_pk_bf16_f32 v117, v126, v127
	v_max_f32_e32 v106, 0, v106
	v_max_f32_e32 v107, 0, v107
	global_store_dwordx4 v[128:129], v[114:117], off offset:256
	s_nop 1
	v_pk_mul_f32 v[116:117], v[106:107], v[106:107]
	v_add_u32_e32 v114, 16, v146
	v_max_f32_e32 v110, 0, v110
	v_max_f32_e32 v111, 0, v111
	v_max_f32_e32 v108, 0, v108
	v_ashrrev_i32_e32 v115, 31, v114
	v_pk_mul_f32 v[110:111], v[110:111], v[110:111]
	v_max_f32_e32 v106, 0, v112
	v_max_f32_e32 v107, 0, v113
	v_max_f32_e32 v109, 0, v109
	v_pk_mul_f32 v[112:113], v[106:107], v[106:107]
	v_cvt_pk_bf16_f32 v106, v110, v111
	v_lshlrev_b64 v[110:111], 13, v[114:115]
	v_pk_mul_f32 v[118:119], v[108:109], v[108:109]
	v_lshl_add_u64 v[110:111], s[42:43], 0, v[110:111]
	v_cvt_pk_bf16_f32 v107, v112, v113
	v_cvt_pk_bf16_f32 v108, v116, v117
	v_cvt_pk_bf16_f32 v109, v118, v119
	v_lshl_add_u64 v[110:111], v[110:111], 0, v[122:123]
	v_max_f32_e32 v98, 0, v98
	v_max_f32_e32 v99, 0, v99
	global_store_dwordx4 v[110:111], v[106:109], off
	s_nop 1
	v_pk_mul_f32 v[106:107], v[98:99], v[98:99]
	v_max_f32_e32 v100, 0, v100
	v_max_f32_e32 v102, 0, v102
	v_max_f32_e32 v103, 0, v103
	v_max_f32_e32 v98, 0, v104
	v_max_f32_e32 v99, 0, v105
	v_max_f32_e32 v101, 0, v101
	v_pk_mul_f32 v[102:103], v[102:103], v[102:103]
	v_pk_mul_f32 v[104:105], v[98:99], v[98:99]
	v_pk_mul_f32 v[108:109], v[100:101], v[100:101]
	v_cvt_pk_bf16_f32 v98, v102, v103
	v_cvt_pk_bf16_f32 v99, v104, v105
	v_cvt_pk_bf16_f32 v100, v106, v107
	v_cvt_pk_bf16_f32 v101, v108, v109
	v_max_f32_e32 v90, 0, v90
	v_max_f32_e32 v91, 0, v91
	global_store_dwordx4 v[110:111], v[98:101], off offset:256
	s_nop 1
	v_pk_mul_f32 v[100:101], v[90:91], v[90:91]
	v_add_u32_e32 v98, 32, v146
	v_max_f32_e32 v94, 0, v94
	v_max_f32_e32 v95, 0, v95
	v_max_f32_e32 v92, 0, v92
	v_ashrrev_i32_e32 v99, 31, v98
	v_pk_mul_f32 v[94:95], v[94:95], v[94:95]
	v_max_f32_e32 v90, 0, v96
	v_max_f32_e32 v91, 0, v97
	v_max_f32_e32 v93, 0, v93
	v_pk_mul_f32 v[96:97], v[90:91], v[90:91]
	v_cvt_pk_bf16_f32 v90, v94, v95
	v_lshlrev_b64 v[94:95], 13, v[98:99]
	v_pk_mul_f32 v[102:103], v[92:93], v[92:93]
	v_lshl_add_u64 v[94:95], s[42:43], 0, v[94:95]
	v_cvt_pk_bf16_f32 v91, v96, v97
	v_cvt_pk_bf16_f32 v92, v100, v101
	v_cvt_pk_bf16_f32 v93, v102, v103
	v_lshl_add_u64 v[94:95], v[94:95], 0, v[122:123]
	v_max_f32_e32 v82, 0, v82
	v_max_f32_e32 v83, 0, v83
	global_store_dwordx4 v[94:95], v[90:93], off
	s_nop 1
	v_pk_mul_f32 v[90:91], v[82:83], v[82:83]
	v_max_f32_e32 v84, 0, v84
	v_max_f32_e32 v86, 0, v86
	v_max_f32_e32 v87, 0, v87
	v_max_f32_e32 v82, 0, v88
	v_max_f32_e32 v83, 0, v89
	v_max_f32_e32 v85, 0, v85
	v_pk_mul_f32 v[86:87], v[86:87], v[86:87]
	v_pk_mul_f32 v[88:89], v[82:83], v[82:83]
	v_pk_mul_f32 v[92:93], v[84:85], v[84:85]
	v_cvt_pk_bf16_f32 v82, v86, v87
	v_cvt_pk_bf16_f32 v83, v88, v89
	v_cvt_pk_bf16_f32 v84, v90, v91
	v_cvt_pk_bf16_f32 v85, v92, v93
	v_max_f32_e32 v74, 0, v74
	v_max_f32_e32 v75, 0, v75
	global_store_dwordx4 v[94:95], v[82:85], off offset:256
	s_nop 1
	v_pk_mul_f32 v[84:85], v[74:75], v[74:75]
	v_add_u32_e32 v82, 48, v146
	v_max_f32_e32 v78, 0, v78
	v_max_f32_e32 v79, 0, v79
	v_max_f32_e32 v76, 0, v76
	v_ashrrev_i32_e32 v83, 31, v82
	v_pk_mul_f32 v[78:79], v[78:79], v[78:79]
	v_max_f32_e32 v74, 0, v80
	v_max_f32_e32 v75, 0, v81
	v_max_f32_e32 v77, 0, v77
	v_pk_mul_f32 v[80:81], v[74:75], v[74:75]
	v_cvt_pk_bf16_f32 v74, v78, v79
	v_lshlrev_b64 v[78:79], 13, v[82:83]
	v_pk_mul_f32 v[86:87], v[76:77], v[76:77]
	v_lshl_add_u64 v[78:79], s[42:43], 0, v[78:79]
	v_cvt_pk_bf16_f32 v75, v80, v81
	v_cvt_pk_bf16_f32 v76, v84, v85
	v_cvt_pk_bf16_f32 v77, v86, v87
	v_lshl_add_u64 v[78:79], v[78:79], 0, v[122:123]
	v_max_f32_e32 v66, 0, v66
	v_max_f32_e32 v67, 0, v67
	global_store_dwordx4 v[78:79], v[74:77], off
	s_nop 1
	v_pk_mul_f32 v[74:75], v[66:67], v[66:67]
	v_max_f32_e32 v68, 0, v68
	v_max_f32_e32 v70, 0, v70
	v_max_f32_e32 v71, 0, v71
	v_max_f32_e32 v66, 0, v72
	v_max_f32_e32 v67, 0, v73
	v_max_f32_e32 v69, 0, v69
	v_pk_mul_f32 v[70:71], v[70:71], v[70:71]
	v_pk_mul_f32 v[72:73], v[66:67], v[66:67]
	v_pk_mul_f32 v[76:77], v[68:69], v[68:69]
	v_cvt_pk_bf16_f32 v66, v70, v71
	v_cvt_pk_bf16_f32 v67, v72, v73
	v_cvt_pk_bf16_f32 v68, v74, v75
	v_cvt_pk_bf16_f32 v69, v76, v77
	v_max_f32_e32 v58, 0, v58
	v_max_f32_e32 v59, 0, v59
	global_store_dwordx4 v[78:79], v[66:69], off offset:256
	s_nop 1
	v_pk_mul_f32 v[68:69], v[58:59], v[58:59]
	v_add_u32_e32 v66, 0x80, v146
	v_max_f32_e32 v62, 0, v62
	v_max_f32_e32 v63, 0, v63
	v_max_f32_e32 v60, 0, v60
	v_ashrrev_i32_e32 v67, 31, v66
	v_pk_mul_f32 v[62:63], v[62:63], v[62:63]
	v_max_f32_e32 v58, 0, v64
	v_max_f32_e32 v59, 0, v65
	v_max_f32_e32 v61, 0, v61
	v_pk_mul_f32 v[64:65], v[58:59], v[58:59]
	v_cvt_pk_bf16_f32 v58, v62, v63
	v_lshlrev_b64 v[62:63], 13, v[66:67]
	v_pk_mul_f32 v[70:71], v[60:61], v[60:61]
	v_lshl_add_u64 v[62:63], s[42:43], 0, v[62:63]
	v_cvt_pk_bf16_f32 v59, v64, v65
	v_cvt_pk_bf16_f32 v60, v68, v69
	v_cvt_pk_bf16_f32 v61, v70, v71
	v_lshl_add_u64 v[62:63], v[62:63], 0, v[122:123]
	v_max_f32_e32 v50, 0, v50
	v_max_f32_e32 v51, 0, v51
	global_store_dwordx4 v[62:63], v[58:61], off
	s_nop 1
	v_pk_mul_f32 v[58:59], v[50:51], v[50:51]
	v_max_f32_e32 v52, 0, v52
	v_max_f32_e32 v54, 0, v54
	v_max_f32_e32 v55, 0, v55
	v_max_f32_e32 v50, 0, v56
	v_max_f32_e32 v51, 0, v57
	v_max_f32_e32 v53, 0, v53
	v_pk_mul_f32 v[54:55], v[54:55], v[54:55]
	v_pk_mul_f32 v[56:57], v[50:51], v[50:51]
	v_pk_mul_f32 v[60:61], v[52:53], v[52:53]
	v_cvt_pk_bf16_f32 v50, v54, v55
	v_cvt_pk_bf16_f32 v51, v56, v57
	v_cvt_pk_bf16_f32 v52, v58, v59
	v_cvt_pk_bf16_f32 v53, v60, v61
	v_max_f32_e32 v42, 0, v42
	v_max_f32_e32 v43, 0, v43
	global_store_dwordx4 v[62:63], v[50:53], off offset:256
	s_nop 1
	v_pk_mul_f32 v[52:53], v[42:43], v[42:43]
	v_add_u32_e32 v50, 0x90, v146
	v_max_f32_e32 v46, 0, v46
	v_max_f32_e32 v47, 0, v47
	v_max_f32_e32 v44, 0, v44
	v_ashrrev_i32_e32 v51, 31, v50
	v_pk_mul_f32 v[46:47], v[46:47], v[46:47]
	v_max_f32_e32 v42, 0, v48
	v_max_f32_e32 v43, 0, v49
	v_max_f32_e32 v45, 0, v45
	v_pk_mul_f32 v[48:49], v[42:43], v[42:43]
	v_cvt_pk_bf16_f32 v42, v46, v47
	v_lshlrev_b64 v[46:47], 13, v[50:51]
	v_pk_mul_f32 v[54:55], v[44:45], v[44:45]
	v_lshl_add_u64 v[46:47], s[42:43], 0, v[46:47]
	v_cvt_pk_bf16_f32 v43, v48, v49
	v_cvt_pk_bf16_f32 v44, v52, v53
	v_cvt_pk_bf16_f32 v45, v54, v55
	v_lshl_add_u64 v[46:47], v[46:47], 0, v[122:123]
	v_max_f32_e32 v34, 0, v34
	v_max_f32_e32 v35, 0, v35
	global_store_dwordx4 v[46:47], v[42:45], off
	s_nop 1
	v_pk_mul_f32 v[42:43], v[34:35], v[34:35]
	v_max_f32_e32 v36, 0, v36
	v_max_f32_e32 v38, 0, v38
	v_max_f32_e32 v39, 0, v39
	v_max_f32_e32 v34, 0, v40
	v_max_f32_e32 v35, 0, v41
	v_max_f32_e32 v37, 0, v37
	v_pk_mul_f32 v[38:39], v[38:39], v[38:39]
	v_pk_mul_f32 v[40:41], v[34:35], v[34:35]
	v_pk_mul_f32 v[44:45], v[36:37], v[36:37]
	v_cvt_pk_bf16_f32 v34, v38, v39
	v_cvt_pk_bf16_f32 v35, v40, v41
	v_cvt_pk_bf16_f32 v36, v42, v43
	v_cvt_pk_bf16_f32 v37, v44, v45
	v_max_f32_e32 v26, 0, v26
	v_max_f32_e32 v27, 0, v27
	global_store_dwordx4 v[46:47], v[34:37], off offset:256
	s_nop 1
	v_pk_mul_f32 v[36:37], v[26:27], v[26:27]
	v_add_u32_e32 v34, 0xa0, v146
	v_max_f32_e32 v30, 0, v30
	v_max_f32_e32 v31, 0, v31
	v_max_f32_e32 v28, 0, v28
	v_ashrrev_i32_e32 v35, 31, v34
	v_pk_mul_f32 v[30:31], v[30:31], v[30:31]
	v_max_f32_e32 v26, 0, v32
	v_max_f32_e32 v27, 0, v33
	v_max_f32_e32 v29, 0, v29
	v_pk_mul_f32 v[32:33], v[26:27], v[26:27]
	v_cvt_pk_bf16_f32 v26, v30, v31
	v_lshlrev_b64 v[30:31], 13, v[34:35]
	v_pk_mul_f32 v[38:39], v[28:29], v[28:29]
	v_lshl_add_u64 v[30:31], s[42:43], 0, v[30:31]
	v_cvt_pk_bf16_f32 v27, v32, v33
	v_cvt_pk_bf16_f32 v28, v36, v37
	v_cvt_pk_bf16_f32 v29, v38, v39
	v_lshl_add_u64 v[30:31], v[30:31], 0, v[122:123]
	v_max_f32_e32 v18, 0, v18
	v_max_f32_e32 v19, 0, v19
	global_store_dwordx4 v[30:31], v[26:29], off
	s_nop 1
	v_pk_mul_f32 v[26:27], v[18:19], v[18:19]
	v_max_f32_e32 v20, 0, v20
	v_max_f32_e32 v22, 0, v22
	v_max_f32_e32 v23, 0, v23
	v_max_f32_e32 v18, 0, v24
	v_max_f32_e32 v19, 0, v25
	v_max_f32_e32 v21, 0, v21
	v_pk_mul_f32 v[22:23], v[22:23], v[22:23]
	v_pk_mul_f32 v[24:25], v[18:19], v[18:19]
	v_pk_mul_f32 v[28:29], v[20:21], v[20:21]
	v_cvt_pk_bf16_f32 v18, v22, v23
	v_cvt_pk_bf16_f32 v19, v24, v25
	v_cvt_pk_bf16_f32 v20, v26, v27
	v_cvt_pk_bf16_f32 v21, v28, v29
	v_max_f32_e32 v10, 0, v10
	v_max_f32_e32 v11, 0, v11
	global_store_dwordx4 v[30:31], v[18:21], off offset:256
	s_nop 1
	v_pk_mul_f32 v[20:21], v[10:11], v[10:11]
	v_add_u32_e32 v18, 0xb0, v146
	v_max_f32_e32 v14, 0, v14
	v_max_f32_e32 v15, 0, v15
	v_max_f32_e32 v12, 0, v12
	v_ashrrev_i32_e32 v19, 31, v18
	v_pk_mul_f32 v[14:15], v[14:15], v[14:15]
	v_max_f32_e32 v10, 0, v16
	v_max_f32_e32 v11, 0, v17
	v_max_f32_e32 v13, 0, v13
	v_pk_mul_f32 v[16:17], v[10:11], v[10:11]
	v_cvt_pk_bf16_f32 v10, v14, v15
	v_lshlrev_b64 v[14:15], 13, v[18:19]
	v_pk_mul_f32 v[22:23], v[12:13], v[12:13]
	v_lshl_add_u64 v[14:15], s[42:43], 0, v[14:15]
	v_cvt_pk_bf16_f32 v11, v16, v17
	v_cvt_pk_bf16_f32 v12, v20, v21
	v_cvt_pk_bf16_f32 v13, v22, v23
	v_lshl_add_u64 v[14:15], v[14:15], 0, v[122:123]
	v_max_f32_e32 v2, 0, v2
	v_max_f32_e32 v3, 0, v3
	global_store_dwordx4 v[14:15], v[10:13], off
	s_nop 1
	v_pk_mul_f32 v[10:11], v[2:3], v[2:3]
	v_max_f32_e32 v4, 0, v4
	v_max_f32_e32 v6, 0, v6
	v_max_f32_e32 v7, 0, v7
	v_max_f32_e32 v2, 0, v8
	v_max_f32_e32 v3, 0, v9
	v_max_f32_e32 v5, 0, v5
	v_pk_mul_f32 v[6:7], v[6:7], v[6:7]
	v_pk_mul_f32 v[8:9], v[2:3], v[2:3]
	v_pk_mul_f32 v[12:13], v[4:5], v[4:5]
	v_cvt_pk_bf16_f32 v2, v6, v7
	v_cvt_pk_bf16_f32 v3, v8, v9
	v_cvt_pk_bf16_f32 v4, v10, v11
	v_cvt_pk_bf16_f32 v5, v12, v13
	s_andn2_b64 vcc, exec, s[4:5]
	s_mov_b64 s[4:5], -1
	global_store_dwordx4 v[14:15], v[2:5], off offset:256
	s_cbranch_vccnz .LBB0_741
	s_andn2_b64 vcc, exec, s[8:9]
	s_cbranch_vccnz .LBB0_740
	s_barrier
	s_branch .LBB0_740

.LBB0_1029:
	s_lshl_b32 s14, s16, 8
	s_and_b32 s43, s14, 0x300
	s_lshl_b32 s14, s2, 8
	s_ashr_i32 s15, s14, 31
	s_lshl_b64 s[14:15], s[14:15], 11
	s_add_u32 s2, s64, s14
	s_addc_u32 s14, s65, s15
	s_lshl_b32 s15, s43, 1
	s_add_u32 s64, s2, s15
	s_addc_u32 s65, s14, 0
	s_add_i32 s2, s6, -1
	s_cmp_gt_u32 s2, 1
	s_mov_b64 s[14:15], -1
	s_cbranch_scc0 .LBB0_1036
	s_cmp_lg_u32 s6, 3
	s_cbranch_scc0 .LBB0_1032
	v_mul_f32_e32 v132, 0xbfb8aa3b, v126
	v_mul_f32_e32 v133, 0xbfb8aa3b, v127
	v_exp_f32_e32 v132, v132
	v_exp_f32_e32 v133, v133
	v_mov_b32_e32 v131, v170
	v_mov_b32_e32 v130, v1
	v_pk_add_f32 v[132:133], v[132:133], 1.0 op_sel_hi:[1,0]
	v_add_u32_e32 v130, s77, v130
	v_lshl_add_u32 v138, v131, 3, s78
	v_ashrrev_i32_e32 v131, 31, v130
	v_lshlrev_b64 v[140:141], 11, v[130:131]
	v_mul_f32_e32 v131, 0xbfb8aa3b, v122
	v_exp_f32_e32 v134, v131
	v_mul_f32_e32 v135, 0xbfb8aa3b, v123
	v_rcp_f32_e32 v131, v133
	v_exp_f32_e32 v135, v135
	v_mul_f32_e32 v131, v127, v131
	v_pk_add_f32 v[134:135], v[134:135], 1.0 op_sel_hi:[1,0]
	v_rcp_f32_e32 v133, v132
	v_lshl_add_u64 v[140:141], s[64:65], 0, v[140:141]
	v_mul_f32_e32 v136, v126, v133
	v_rcp_f32_e32 v132, v135
	s_nop 0
	v_mul_f32_e32 v139, v123, v132
	v_mul_f32_e32 v132, 0xbfb8aa3b, v128
	v_mul_f32_e32 v133, 0xbfb8aa3b, v129
	v_exp_f32_e32 v132, v132
	v_exp_f32_e32 v133, v133
	v_rcp_f32_e32 v135, v134
	v_pk_add_f32 v[132:133], v[132:133], 1.0 op_sel_hi:[1,0]
	v_mul_f32_e32 v143, v122, v135
	v_mul_f32_e32 v134, 0xbfb8aa3b, v124
	v_exp_f32_e32 v134, v134
	v_rcp_f32_e32 v135, v133
	s_nop 0
	v_mul_f32_e32 v133, v129, v135
	v_mul_f32_e32 v135, 0xbfb8aa3b, v125
	v_exp_f32_e32 v135, v135
	s_nop 0
	v_pk_add_f32 v[134:135], v[134:135], 1.0 op_sel_hi:[1,0]
	v_rcp_f32_e32 v137, v132
	s_nop 0
	v_mul_f32_e32 v132, v128, v137
	v_rcp_f32_e32 v137, v135
	v_rcp_f32_e32 v135, v134
	v_mul_f32_e32 v137, v125, v137
	v_mul_f32_e32 v142, v124, v135
	v_cvt_pk_bf16_f32 v134, v136, v131
	v_mul_f32_e32 v131, 0xbfb8aa3b, v118
	v_cvt_pk_bf16_f32 v137, v142, v137
	v_exp_f32_e32 v142, v131
	v_mul_f32_e32 v131, 0xbfb8aa3b, v119
	v_cvt_pk_bf16_f32 v136, v143, v139
	v_exp_f32_e32 v143, v131
	v_ashrrev_i32_e32 v139, 31, v138
	v_cvt_pk_bf16_f32 v135, v132, v133
	v_lshlrev_b64 v[132:133], 1, v[138:139]
	v_lshl_add_u64 v[138:139], v[140:141], 0, v[132:133]
	v_pk_add_f32 v[140:141], v[142:143], 1.0 op_sel_hi:[1,0]
	global_store_dwordx4 v[138:139], v[134:137], off
	s_nop 1
	v_mul_f32_e32 v134, 0xbfb8aa3b, v114
	v_exp_f32_e32 v134, v134
	v_rcp_f32_e32 v131, v141
	v_mul_f32_e32 v135, 0xbfb8aa3b, v115
	v_exp_f32_e32 v135, v135
	v_mul_f32_e32 v131, v119, v131
	v_pk_add_f32 v[134:135], v[134:135], 1.0 op_sel_hi:[1,0]
	v_rcp_f32_e32 v136, v140
	s_nop 0
	v_mul_f32_e32 v140, v118, v136
	v_rcp_f32_e32 v136, v135
	s_nop 0
	v_mul_f32_e32 v141, v115, v136
	v_mul_f32_e32 v136, 0xbfb8aa3b, v120
	v_mul_f32_e32 v137, 0xbfb8aa3b, v121
	v_exp_f32_e32 v136, v136
	v_exp_f32_e32 v137, v137
	v_rcp_f32_e32 v135, v134
	v_pk_add_f32 v[136:137], v[136:137], 1.0 op_sel_hi:[1,0]
	v_mul_f32_e32 v144, v114, v135
	v_mul_f32_e32 v134, 0xbfb8aa3b, v116
	v_exp_f32_e32 v134, v134
	v_rcp_f32_e32 v135, v137
	s_nop 0
	v_mul_f32_e32 v137, v121, v135
	v_mul_f32_e32 v135, 0xbfb8aa3b, v117
	v_exp_f32_e32 v135, v135
	s_nop 0
	v_pk_add_f32 v[134:135], v[134:135], 1.0 op_sel_hi:[1,0]
	v_rcp_f32_e32 v142, v136
	s_nop 0
	v_mul_f32_e32 v136, v120, v142
	v_rcp_f32_e32 v142, v135
	v_rcp_f32_e32 v135, v134
	v_mul_f32_e32 v142, v117, v142
	v_mul_f32_e32 v143, v116, v135
	v_cvt_pk_bf16_f32 v134, v140, v131
	v_mul_f32_e32 v131, 0xbfb8aa3b, v110
	v_exp_f32_e32 v140, v131
	v_mul_f32_e32 v131, 0xbfb8aa3b, v111
	v_cvt_pk_bf16_f32 v135, v136, v137
	v_cvt_pk_bf16_f32 v136, v144, v141
	v_exp_f32_e32 v141, v131
	v_cvt_pk_bf16_f32 v137, v143, v142
	global_store_dwordx4 v[138:139], v[134:137], off offset:256
	s_nop 1
	s_nop 0
	v_pk_add_f32 v[136:137], v[140:141], 1.0 op_sel_hi:[1,0]
	v_add_u32_e32 v134, 16, v130
	v_ashrrev_i32_e32 v135, 31, v134
	v_lshlrev_b64 v[138:139], 11, v[134:135]
	v_mul_f32_e32 v134, 0xbfb8aa3b, v106
	v_exp_f32_e32 v134, v134
	v_rcp_f32_e32 v131, v137
	v_mul_f32_e32 v135, 0xbfb8aa3b, v107
	v_exp_f32_e32 v135, v135
	v_mul_f32_e32 v131, v111, v131
	v_pk_add_f32 v[134:135], v[134:135], 1.0 op_sel_hi:[1,0]
	v_rcp_f32_e32 v137, v136
	v_lshl_add_u64 v[138:139], s[64:65], 0, v[138:139]
	v_mul_f32_e32 v140, v110, v137
	v_rcp_f32_e32 v136, v135
	v_mul_f32_e32 v137, 0xbfb8aa3b, v113
	v_mul_f32_e32 v142, v107, v136
	v_mul_f32_e32 v136, 0xbfb8aa3b, v112
	v_exp_f32_e32 v136, v136
	v_exp_f32_e32 v137, v137
	v_rcp_f32_e32 v135, v134
	v_pk_add_f32 v[136:137], v[136:137], 1.0 op_sel_hi:[1,0]
	v_mul_f32_e32 v144, v106, v135
	v_mul_f32_e32 v134, 0xbfb8aa3b, v108
	v_exp_f32_e32 v134, v134
	v_lshl_add_u64 v[138:139], v[138:139], 0, v[132:133]
	v_rcp_f32_e32 v135, v137
	s_nop 0
	v_mul_f32_e32 v137, v113, v135
	v_mul_f32_e32 v135, 0xbfb8aa3b, v109
	v_exp_f32_e32 v135, v135
	s_nop 0
	v_pk_add_f32 v[134:135], v[134:135], 1.0 op_sel_hi:[1,0]
	v_rcp_f32_e32 v141, v136
	s_nop 0
	v_mul_f32_e32 v136, v112, v141
	v_rcp_f32_e32 v141, v135
	v_rcp_f32_e32 v135, v134
	v_mul_f32_e32 v145, v109, v141
	v_mul_f32_e32 v143, v108, v135
	v_cvt_pk_bf16_f32 v134, v140, v131
	v_mul_f32_e32 v131, 0xbfb8aa3b, v102
	v_exp_f32_e32 v140, v131
	v_mul_f32_e32 v131, 0xbfb8aa3b, v103
	v_exp_f32_e32 v141, v131
	v_cvt_pk_bf16_f32 v135, v136, v137
	v_cvt_pk_bf16_f32 v136, v144, v142
	v_cvt_pk_bf16_f32 v137, v143, v145
	v_pk_add_f32 v[140:141], v[140:141], 1.0 op_sel_hi:[1,0]
	global_store_dwordx4 v[138:139], v[134:137], off
	s_nop 1
	v_mul_f32_e32 v134, 0xbfb8aa3b, v98
	v_exp_f32_e32 v134, v134
	v_rcp_f32_e32 v131, v141
	v_mul_f32_e32 v135, 0xbfb8aa3b, v99
	v_exp_f32_e32 v135, v135
	v_mul_f32_e32 v131, v103, v131
	v_pk_add_f32 v[134:135], v[134:135], 1.0 op_sel_hi:[1,0]
	v_rcp_f32_e32 v136, v140
	s_nop 0
	v_mul_f32_e32 v140, v102, v136
	v_rcp_f32_e32 v136, v135
	s_nop 0
	v_mul_f32_e32 v141, v99, v136
	v_mul_f32_e32 v136, 0xbfb8aa3b, v104
	v_mul_f32_e32 v137, 0xbfb8aa3b, v105
	v_exp_f32_e32 v136, v136
	v_exp_f32_e32 v137, v137
	v_rcp_f32_e32 v135, v134
	v_pk_add_f32 v[136:137], v[136:137], 1.0 op_sel_hi:[1,0]
	v_mul_f32_e32 v144, v98, v135
	v_mul_f32_e32 v134, 0xbfb8aa3b, v100
	v_exp_f32_e32 v134, v134
	v_rcp_f32_e32 v135, v137
	s_nop 0
	v_mul_f32_e32 v137, v105, v135
	v_mul_f32_e32 v135, 0xbfb8aa3b, v101
	v_exp_f32_e32 v135, v135
	s_nop 0
	v_pk_add_f32 v[134:135], v[134:135], 1.0 op_sel_hi:[1,0]
	v_rcp_f32_e32 v142, v136
	s_nop 0
	v_mul_f32_e32 v136, v104, v142
	v_rcp_f32_e32 v142, v135
	v_rcp_f32_e32 v135, v134
	v_mul_f32_e32 v142, v101, v142
	v_mul_f32_e32 v143, v100, v135
	v_cvt_pk_bf16_f32 v134, v140, v131
	v_mul_f32_e32 v131, 0xbfb8aa3b, v94
	v_exp_f32_e32 v140, v131
	v_mul_f32_e32 v131, 0xbfb8aa3b, v95
	v_cvt_pk_bf16_f32 v135, v136, v137
	v_cvt_pk_bf16_f32 v136, v144, v141
	v_exp_f32_e32 v141, v131
	v_cvt_pk_bf16_f32 v137, v143, v142
	global_store_dwordx4 v[138:139], v[134:137], off offset:256
	s_nop 1
	s_nop 0
	v_pk_add_f32 v[136:137], v[140:141], 1.0 op_sel_hi:[1,0]
	v_add_u32_e32 v134, 32, v130
	v_ashrrev_i32_e32 v135, 31, v134
	v_lshlrev_b64 v[138:139], 11, v[134:135]
	v_mul_f32_e32 v134, 0xbfb8aa3b, v90
	v_exp_f32_e32 v134, v134
	v_rcp_f32_e32 v131, v137
	v_mul_f32_e32 v135, 0xbfb8aa3b, v91
	v_exp_f32_e32 v135, v135
	v_mul_f32_e32 v131, v95, v131
	v_pk_add_f32 v[134:135], v[134:135], 1.0 op_sel_hi:[1,0]
	v_rcp_f32_e32 v137, v136
	v_lshl_add_u64 v[138:139], s[64:65], 0, v[138:139]
	v_mul_f32_e32 v140, v94, v137
	v_rcp_f32_e32 v136, v135
	v_mul_f32_e32 v137, 0xbfb8aa3b, v97
	v_mul_f32_e32 v142, v91, v136
	v_mul_f32_e32 v136, 0xbfb8aa3b, v96
	v_exp_f32_e32 v136, v136
	v_exp_f32_e32 v137, v137
	v_rcp_f32_e32 v135, v134
	v_pk_add_f32 v[136:137], v[136:137], 1.0 op_sel_hi:[1,0]
	v_mul_f32_e32 v144, v90, v135
	v_mul_f32_e32 v134, 0xbfb8aa3b, v92
	v_exp_f32_e32 v134, v134
	v_lshl_add_u64 v[138:139], v[138:139], 0, v[132:133]
	v_rcp_f32_e32 v135, v137
	s_nop 0
	v_mul_f32_e32 v137, v97, v135
	v_mul_f32_e32 v135, 0xbfb8aa3b, v93
	v_exp_f32_e32 v135, v135
	s_nop 0
	v_pk_add_f32 v[134:135], v[134:135], 1.0 op_sel_hi:[1,0]
	v_rcp_f32_e32 v141, v136
	s_nop 0
	v_mul_f32_e32 v136, v96, v141
	v_rcp_f32_e32 v141, v135
	v_rcp_f32_e32 v135, v134
	v_mul_f32_e32 v145, v93, v141
	v_mul_f32_e32 v143, v92, v135
	v_cvt_pk_bf16_f32 v134, v140, v131
	v_mul_f32_e32 v131, 0xbfb8aa3b, v86
	v_exp_f32_e32 v140, v131
	v_mul_f32_e32 v131, 0xbfb8aa3b, v87
	v_exp_f32_e32 v141, v131
	v_cvt_pk_bf16_f32 v135, v136, v137
	v_cvt_pk_bf16_f32 v136, v144, v142
	v_cvt_pk_bf16_f32 v137, v143, v145
	v_pk_add_f32 v[140:141], v[140:141], 1.0 op_sel_hi:[1,0]
	global_store_dwordx4 v[138:139], v[134:137], off
	s_nop 1
	v_mul_f32_e32 v134, 0xbfb8aa3b, v82
	v_exp_f32_e32 v134, v134
	v_rcp_f32_e32 v131, v141
	v_mul_f32_e32 v135, 0xbfb8aa3b, v83
	v_exp_f32_e32 v135, v135
	v_mul_f32_e32 v131, v87, v131
	v_pk_add_f32 v[134:135], v[134:135], 1.0 op_sel_hi:[1,0]
	v_rcp_f32_e32 v136, v140
	s_nop 0
	v_mul_f32_e32 v140, v86, v136
	v_rcp_f32_e32 v136, v135
	s_nop 0
	v_mul_f32_e32 v141, v83, v136
	v_mul_f32_e32 v136, 0xbfb8aa3b, v88
	v_mul_f32_e32 v137, 0xbfb8aa3b, v89
	v_exp_f32_e32 v136, v136
	v_exp_f32_e32 v137, v137
	v_rcp_f32_e32 v135, v134
	v_pk_add_f32 v[136:137], v[136:137], 1.0 op_sel_hi:[1,0]
	v_mul_f32_e32 v144, v82, v135
	v_mul_f32_e32 v134, 0xbfb8aa3b, v84
	v_exp_f32_e32 v134, v134
	v_rcp_f32_e32 v135, v137
	s_nop 0
	v_mul_f32_e32 v137, v89, v135
	v_mul_f32_e32 v135, 0xbfb8aa3b, v85
	v_exp_f32_e32 v135, v135
	s_nop 0
	v_pk_add_f32 v[134:135], v[134:135], 1.0 op_sel_hi:[1,0]
	v_rcp_f32_e32 v142, v136
	s_nop 0
	v_mul_f32_e32 v136, v88, v142
	v_rcp_f32_e32 v142, v135
	v_rcp_f32_e32 v135, v134
	v_mul_f32_e32 v142, v85, v142
	v_mul_f32_e32 v143, v84, v135
	v_cvt_pk_bf16_f32 v134, v140, v131
	v_mul_f32_e32 v131, 0xbfb8aa3b, v78
	v_exp_f32_e32 v140, v131
	v_mul_f32_e32 v131, 0xbfb8aa3b, v79
	v_cvt_pk_bf16_f32 v135, v136, v137
	v_cvt_pk_bf16_f32 v136, v144, v141
	v_exp_f32_e32 v141, v131
	v_cvt_pk_bf16_f32 v137, v143, v142
	global_store_dwordx4 v[138:139], v[134:137], off offset:256
	s_nop 1
	s_nop 0
	v_pk_add_f32 v[136:137], v[140:141], 1.0 op_sel_hi:[1,0]
	v_add_u32_e32 v134, 48, v130
	v_ashrrev_i32_e32 v135, 31, v134
	v_lshlrev_b64 v[138:139], 11, v[134:135]
	v_mul_f32_e32 v134, 0xbfb8aa3b, v74
	v_exp_f32_e32 v134, v134
	v_rcp_f32_e32 v131, v137
	v_mul_f32_e32 v135, 0xbfb8aa3b, v75
	v_exp_f32_e32 v135, v135
	v_mul_f32_e32 v131, v79, v131
	v_pk_add_f32 v[134:135], v[134:135], 1.0 op_sel_hi:[1,0]
	v_rcp_f32_e32 v137, v136
	v_lshl_add_u64 v[138:139], s[64:65], 0, v[138:139]
	v_mul_f32_e32 v140, v78, v137
	v_rcp_f32_e32 v136, v135
	v_mul_f32_e32 v137, 0xbfb8aa3b, v81
	v_mul_f32_e32 v142, v75, v136
	v_mul_f32_e32 v136, 0xbfb8aa3b, v80
	v_exp_f32_e32 v136, v136
	v_exp_f32_e32 v137, v137
	v_rcp_f32_e32 v135, v134
	v_pk_add_f32 v[136:137], v[136:137], 1.0 op_sel_hi:[1,0]
	v_mul_f32_e32 v144, v74, v135
	v_mul_f32_e32 v134, 0xbfb8aa3b, v76
	v_exp_f32_e32 v134, v134
	v_lshl_add_u64 v[138:139], v[138:139], 0, v[132:133]
	v_rcp_f32_e32 v135, v137
	s_nop 0
	v_mul_f32_e32 v137, v81, v135
	v_mul_f32_e32 v135, 0xbfb8aa3b, v77
	v_exp_f32_e32 v135, v135
	s_nop 0
	v_pk_add_f32 v[134:135], v[134:135], 1.0 op_sel_hi:[1,0]
	v_rcp_f32_e32 v141, v136
	s_nop 0
	v_mul_f32_e32 v136, v80, v141
	v_rcp_f32_e32 v141, v135
	v_rcp_f32_e32 v135, v134
	v_mul_f32_e32 v145, v77, v141
	v_mul_f32_e32 v143, v76, v135
	v_cvt_pk_bf16_f32 v134, v140, v131
	v_mul_f32_e32 v131, 0xbfb8aa3b, v70
	v_exp_f32_e32 v140, v131
	v_mul_f32_e32 v131, 0xbfb8aa3b, v71
	v_exp_f32_e32 v141, v131
	v_cvt_pk_bf16_f32 v135, v136, v137
	v_cvt_pk_bf16_f32 v136, v144, v142
	v_cvt_pk_bf16_f32 v137, v143, v145
	v_pk_add_f32 v[140:141], v[140:141], 1.0 op_sel_hi:[1,0]
	global_store_dwordx4 v[138:139], v[134:137], off
	s_nop 1
	v_mul_f32_e32 v134, 0xbfb8aa3b, v66
	v_exp_f32_e32 v134, v134
	v_rcp_f32_e32 v131, v141
	v_mul_f32_e32 v135, 0xbfb8aa3b, v67
	v_exp_f32_e32 v135, v135
	v_mul_f32_e32 v131, v71, v131
	v_pk_add_f32 v[134:135], v[134:135], 1.0 op_sel_hi:[1,0]
	v_rcp_f32_e32 v136, v140
	s_nop 0
	v_mul_f32_e32 v140, v70, v136
	v_rcp_f32_e32 v136, v135
	s_nop 0
	v_mul_f32_e32 v141, v67, v136
	v_mul_f32_e32 v136, 0xbfb8aa3b, v72
	v_mul_f32_e32 v137, 0xbfb8aa3b, v73
	v_exp_f32_e32 v136, v136
	v_exp_f32_e32 v137, v137
	v_rcp_f32_e32 v135, v134
	v_pk_add_f32 v[136:137], v[136:137], 1.0 op_sel_hi:[1,0]
	v_mul_f32_e32 v144, v66, v135
	v_mul_f32_e32 v134, 0xbfb8aa3b, v68
	v_exp_f32_e32 v134, v134
	v_rcp_f32_e32 v135, v137
	s_nop 0
	v_mul_f32_e32 v137, v73, v135
	v_mul_f32_e32 v135, 0xbfb8aa3b, v69
	v_exp_f32_e32 v135, v135
	s_nop 0
	v_pk_add_f32 v[134:135], v[134:135], 1.0 op_sel_hi:[1,0]
	v_rcp_f32_e32 v142, v136
	s_nop 0
	v_mul_f32_e32 v136, v72, v142
	v_rcp_f32_e32 v142, v135
	v_rcp_f32_e32 v135, v134
	v_mul_f32_e32 v142, v69, v142
	v_mul_f32_e32 v143, v68, v135
	v_cvt_pk_bf16_f32 v134, v140, v131
	v_mul_f32_e32 v131, 0xbfb8aa3b, v62
	v_exp_f32_e32 v140, v131
	v_mul_f32_e32 v131, 0xbfb8aa3b, v63
	v_cvt_pk_bf16_f32 v135, v136, v137
	v_cvt_pk_bf16_f32 v136, v144, v141
	v_exp_f32_e32 v141, v131
	v_cvt_pk_bf16_f32 v137, v143, v142
	global_store_dwordx4 v[138:139], v[134:137], off offset:256
	s_nop 1
	s_nop 0
	v_pk_add_f32 v[136:137], v[140:141], 1.0 op_sel_hi:[1,0]
	v_add_u32_e32 v134, 0x80, v130
	v_ashrrev_i32_e32 v135, 31, v134
	v_lshlrev_b64 v[138:139], 11, v[134:135]
	v_mul_f32_e32 v134, 0xbfb8aa3b, v58
	v_exp_f32_e32 v134, v134
	v_rcp_f32_e32 v131, v137
	v_mul_f32_e32 v135, 0xbfb8aa3b, v59
	v_exp_f32_e32 v135, v135
	v_mul_f32_e32 v131, v63, v131
	v_pk_add_f32 v[134:135], v[134:135], 1.0 op_sel_hi:[1,0]
	v_rcp_f32_e32 v137, v136
	v_lshl_add_u64 v[138:139], s[64:65], 0, v[138:139]
	v_mul_f32_e32 v140, v62, v137
	v_rcp_f32_e32 v136, v135
	v_mul_f32_e32 v137, 0xbfb8aa3b, v65
	v_mul_f32_e32 v142, v59, v136
	v_mul_f32_e32 v136, 0xbfb8aa3b, v64
	v_exp_f32_e32 v136, v136
	v_exp_f32_e32 v137, v137
	v_rcp_f32_e32 v135, v134
	v_pk_add_f32 v[136:137], v[136:137], 1.0 op_sel_hi:[1,0]
	v_mul_f32_e32 v144, v58, v135
	v_mul_f32_e32 v134, 0xbfb8aa3b, v60
	v_exp_f32_e32 v134, v134
	v_lshl_add_u64 v[138:139], v[138:139], 0, v[132:133]
	v_rcp_f32_e32 v135, v137
	s_nop 0
	v_mul_f32_e32 v137, v65, v135
	v_mul_f32_e32 v135, 0xbfb8aa3b, v61
	v_exp_f32_e32 v135, v135
	s_nop 0
	v_pk_add_f32 v[134:135], v[134:135], 1.0 op_sel_hi:[1,0]
	v_rcp_f32_e32 v141, v136
	s_nop 0
	v_mul_f32_e32 v136, v64, v141
	v_rcp_f32_e32 v141, v135
	v_rcp_f32_e32 v135, v134
	v_mul_f32_e32 v145, v61, v141
	v_mul_f32_e32 v143, v60, v135
	v_cvt_pk_bf16_f32 v134, v140, v131
	v_mul_f32_e32 v131, 0xbfb8aa3b, v54
	v_exp_f32_e32 v140, v131
	v_mul_f32_e32 v131, 0xbfb8aa3b, v55
	v_exp_f32_e32 v141, v131
	v_cvt_pk_bf16_f32 v135, v136, v137
	v_cvt_pk_bf16_f32 v136, v144, v142
	v_cvt_pk_bf16_f32 v137, v143, v145
	v_pk_add_f32 v[140:141], v[140:141], 1.0 op_sel_hi:[1,0]
	global_store_dwordx4 v[138:139], v[134:137], off
	s_nop 1
	v_mul_f32_e32 v134, 0xbfb8aa3b, v50
	v_exp_f32_e32 v134, v134
	v_rcp_f32_e32 v131, v141
	v_mul_f32_e32 v135, 0xbfb8aa3b, v51
	v_exp_f32_e32 v135, v135
	v_mul_f32_e32 v131, v55, v131
	v_pk_add_f32 v[134:135], v[134:135], 1.0 op_sel_hi:[1,0]
	v_rcp_f32_e32 v136, v140
	s_nop 0
	v_mul_f32_e32 v140, v54, v136
	v_rcp_f32_e32 v136, v135
	s_nop 0
	v_mul_f32_e32 v141, v51, v136
	v_mul_f32_e32 v136, 0xbfb8aa3b, v56
	v_mul_f32_e32 v137, 0xbfb8aa3b, v57
	v_exp_f32_e32 v136, v136
	v_exp_f32_e32 v137, v137
	v_rcp_f32_e32 v135, v134
	v_pk_add_f32 v[136:137], v[136:137], 1.0 op_sel_hi:[1,0]
	v_mul_f32_e32 v144, v50, v135
	v_mul_f32_e32 v134, 0xbfb8aa3b, v52
	v_exp_f32_e32 v134, v134
	v_rcp_f32_e32 v135, v137
	s_nop 0
	v_mul_f32_e32 v137, v57, v135
	v_mul_f32_e32 v135, 0xbfb8aa3b, v53
	v_exp_f32_e32 v135, v135
	s_nop 0
	v_pk_add_f32 v[134:135], v[134:135], 1.0 op_sel_hi:[1,0]
	v_rcp_f32_e32 v142, v136
	s_nop 0
	v_mul_f32_e32 v136, v56, v142
	v_rcp_f32_e32 v142, v135
	v_rcp_f32_e32 v135, v134
	v_mul_f32_e32 v142, v53, v142
	v_mul_f32_e32 v143, v52, v135
	v_cvt_pk_bf16_f32 v134, v140, v131
	v_mul_f32_e32 v131, 0xbfb8aa3b, v46
	v_exp_f32_e32 v140, v131
	v_mul_f32_e32 v131, 0xbfb8aa3b, v47
	v_cvt_pk_bf16_f32 v135, v136, v137
	v_cvt_pk_bf16_f32 v136, v144, v141
	v_exp_f32_e32 v141, v131
	v_cvt_pk_bf16_f32 v137, v143, v142
	global_store_dwordx4 v[138:139], v[134:137], off offset:256
	s_nop 1
	s_nop 0
	v_pk_add_f32 v[136:137], v[140:141], 1.0 op_sel_hi:[1,0]
	v_add_u32_e32 v134, 0x90, v130
	v_ashrrev_i32_e32 v135, 31, v134
	v_lshlrev_b64 v[138:139], 11, v[134:135]
	v_mul_f32_e32 v134, 0xbfb8aa3b, v42
	v_exp_f32_e32 v134, v134
	v_rcp_f32_e32 v131, v137
	v_mul_f32_e32 v135, 0xbfb8aa3b, v43
	v_exp_f32_e32 v135, v135
	v_mul_f32_e32 v131, v47, v131
	v_pk_add_f32 v[134:135], v[134:135], 1.0 op_sel_hi:[1,0]
	v_rcp_f32_e32 v137, v136
	v_lshl_add_u64 v[138:139], s[64:65], 0, v[138:139]
	v_mul_f32_e32 v140, v46, v137
	v_rcp_f32_e32 v136, v135
	v_mul_f32_e32 v137, 0xbfb8aa3b, v49
	v_mul_f32_e32 v142, v43, v136
	v_mul_f32_e32 v136, 0xbfb8aa3b, v48
	v_exp_f32_e32 v136, v136
	v_exp_f32_e32 v137, v137
	v_rcp_f32_e32 v135, v134
	v_pk_add_f32 v[136:137], v[136:137], 1.0 op_sel_hi:[1,0]
	v_mul_f32_e32 v144, v42, v135
	v_mul_f32_e32 v134, 0xbfb8aa3b, v44
	v_exp_f32_e32 v134, v134
	v_lshl_add_u64 v[138:139], v[138:139], 0, v[132:133]
	v_rcp_f32_e32 v135, v137
	s_nop 0
	v_mul_f32_e32 v137, v49, v135
	v_mul_f32_e32 v135, 0xbfb8aa3b, v45
	v_exp_f32_e32 v135, v135
	s_nop 0
	v_pk_add_f32 v[134:135], v[134:135], 1.0 op_sel_hi:[1,0]
	v_rcp_f32_e32 v141, v136
	s_nop 0
	v_mul_f32_e32 v136, v48, v141
	v_rcp_f32_e32 v141, v135
	v_rcp_f32_e32 v135, v134
	v_mul_f32_e32 v145, v45, v141
	v_mul_f32_e32 v143, v44, v135
	v_cvt_pk_bf16_f32 v134, v140, v131
	v_mul_f32_e32 v131, 0xbfb8aa3b, v38
	v_exp_f32_e32 v140, v131
	v_mul_f32_e32 v131, 0xbfb8aa3b, v39
	v_exp_f32_e32 v141, v131
	v_cvt_pk_bf16_f32 v135, v136, v137
	v_cvt_pk_bf16_f32 v136, v144, v142
	v_cvt_pk_bf16_f32 v137, v143, v145
	v_pk_add_f32 v[140:141], v[140:141], 1.0 op_sel_hi:[1,0]
	global_store_dwordx4 v[138:139], v[134:137], off
	s_nop 1
	v_mul_f32_e32 v134, 0xbfb8aa3b, v34
	v_exp_f32_e32 v134, v134
	v_rcp_f32_e32 v131, v141
	v_mul_f32_e32 v135, 0xbfb8aa3b, v35
	v_exp_f32_e32 v135, v135
	v_mul_f32_e32 v131, v39, v131
	v_pk_add_f32 v[134:135], v[134:135], 1.0 op_sel_hi:[1,0]
	v_rcp_f32_e32 v136, v140
	s_nop 0
	v_mul_f32_e32 v140, v38, v136
	v_rcp_f32_e32 v136, v135
	s_nop 0
	v_mul_f32_e32 v141, v35, v136
	v_mul_f32_e32 v136, 0xbfb8aa3b, v40
	v_mul_f32_e32 v137, 0xbfb8aa3b, v41
	v_exp_f32_e32 v136, v136
	v_exp_f32_e32 v137, v137
	v_rcp_f32_e32 v135, v134
	v_pk_add_f32 v[136:137], v[136:137], 1.0 op_sel_hi:[1,0]
	v_mul_f32_e32 v144, v34, v135
	v_mul_f32_e32 v134, 0xbfb8aa3b, v36
	v_exp_f32_e32 v134, v134
	v_rcp_f32_e32 v135, v137
	s_nop 0
	v_mul_f32_e32 v137, v41, v135
	v_mul_f32_e32 v135, 0xbfb8aa3b, v37
	v_exp_f32_e32 v135, v135
	s_nop 0
	v_pk_add_f32 v[134:135], v[134:135], 1.0 op_sel_hi:[1,0]
	v_rcp_f32_e32 v142, v136
	s_nop 0
	v_mul_f32_e32 v136, v40, v142
	v_rcp_f32_e32 v142, v135
	v_rcp_f32_e32 v135, v134
	v_mul_f32_e32 v142, v37, v142
	v_mul_f32_e32 v143, v36, v135
	v_cvt_pk_bf16_f32 v134, v140, v131
	v_mul_f32_e32 v131, 0xbfb8aa3b, v30
	v_exp_f32_e32 v140, v131
	v_mul_f32_e32 v131, 0xbfb8aa3b, v31
	v_cvt_pk_bf16_f32 v135, v136, v137
	v_cvt_pk_bf16_f32 v136, v144, v141
	v_exp_f32_e32 v141, v131
	v_cvt_pk_bf16_f32 v137, v143, v142
	global_store_dwordx4 v[138:139], v[134:137], off offset:256
	s_nop 1
	s_nop 0
	v_pk_add_f32 v[136:137], v[140:141], 1.0 op_sel_hi:[1,0]
	v_add_u32_e32 v134, 0xa0, v130
	v_ashrrev_i32_e32 v135, 31, v134
	v_lshlrev_b64 v[138:139], 11, v[134:135]
	v_mul_f32_e32 v134, 0xbfb8aa3b, v26
	v_exp_f32_e32 v134, v134
	v_rcp_f32_e32 v131, v137
	v_mul_f32_e32 v135, 0xbfb8aa3b, v27
	v_exp_f32_e32 v135, v135
	v_mul_f32_e32 v131, v31, v131
	v_pk_add_f32 v[134:135], v[134:135], 1.0 op_sel_hi:[1,0]
	v_rcp_f32_e32 v137, v136
	v_lshl_add_u64 v[138:139], s[64:65], 0, v[138:139]
	v_mul_f32_e32 v140, v30, v137
	v_rcp_f32_e32 v136, v135
	v_mul_f32_e32 v137, 0xbfb8aa3b, v33
	v_mul_f32_e32 v142, v27, v136
	v_mul_f32_e32 v136, 0xbfb8aa3b, v32
	v_exp_f32_e32 v136, v136
	v_exp_f32_e32 v137, v137
	v_rcp_f32_e32 v135, v134
	v_pk_add_f32 v[136:137], v[136:137], 1.0 op_sel_hi:[1,0]
	v_mul_f32_e32 v144, v26, v135
	v_mul_f32_e32 v134, 0xbfb8aa3b, v28
	v_exp_f32_e32 v134, v134
	v_lshl_add_u64 v[138:139], v[138:139], 0, v[132:133]
	v_add_u32_e32 v130, 0xb0, v130
	v_rcp_f32_e32 v135, v137
	s_nop 0
	v_mul_f32_e32 v137, v33, v135
	v_mul_f32_e32 v135, 0xbfb8aa3b, v29
	v_exp_f32_e32 v135, v135
	s_nop 0
	v_pk_add_f32 v[134:135], v[134:135], 1.0 op_sel_hi:[1,0]
	v_rcp_f32_e32 v141, v136
	s_nop 0
	v_mul_f32_e32 v136, v32, v141
	v_rcp_f32_e32 v141, v135
	v_rcp_f32_e32 v135, v134
	v_mul_f32_e32 v145, v29, v141
	v_mul_f32_e32 v143, v28, v135
	v_cvt_pk_bf16_f32 v134, v140, v131
	v_mul_f32_e32 v131, 0xbfb8aa3b, v22
	v_exp_f32_e32 v140, v131
	v_mul_f32_e32 v131, 0xbfb8aa3b, v23
	v_exp_f32_e32 v141, v131
	v_cvt_pk_bf16_f32 v135, v136, v137
	v_cvt_pk_bf16_f32 v136, v144, v142
	v_cvt_pk_bf16_f32 v137, v143, v145
	v_pk_add_f32 v[140:141], v[140:141], 1.0 op_sel_hi:[1,0]
	global_store_dwordx4 v[138:139], v[134:137], off
	s_nop 1
	v_mul_f32_e32 v134, 0xbfb8aa3b, v18
	v_exp_f32_e32 v134, v134
	v_rcp_f32_e32 v131, v141
	v_mul_f32_e32 v135, 0xbfb8aa3b, v19
	v_exp_f32_e32 v135, v135
	v_mul_f32_e32 v131, v23, v131
	v_pk_add_f32 v[134:135], v[134:135], 1.0 op_sel_hi:[1,0]
	v_rcp_f32_e32 v136, v140
	s_nop 0
	v_mul_f32_e32 v140, v22, v136
	v_rcp_f32_e32 v136, v135
	s_nop 0
	v_mul_f32_e32 v141, v19, v136
	v_mul_f32_e32 v136, 0xbfb8aa3b, v24
	v_mul_f32_e32 v137, 0xbfb8aa3b, v25
	v_exp_f32_e32 v136, v136
	v_exp_f32_e32 v137, v137
	v_rcp_f32_e32 v135, v134
	v_pk_add_f32 v[136:137], v[136:137], 1.0 op_sel_hi:[1,0]
	v_mul_f32_e32 v144, v18, v135
	v_mul_f32_e32 v134, 0xbfb8aa3b, v20
	v_exp_f32_e32 v134, v134
	v_rcp_f32_e32 v135, v137
	s_nop 0
	v_mul_f32_e32 v137, v25, v135
	v_mul_f32_e32 v135, 0xbfb8aa3b, v21
	v_exp_f32_e32 v135, v135
	s_nop 0
	v_pk_add_f32 v[134:135], v[134:135], 1.0 op_sel_hi:[1,0]
	v_rcp_f32_e32 v142, v136
	s_nop 0
	v_mul_f32_e32 v136, v24, v142
	v_rcp_f32_e32 v142, v135
	v_rcp_f32_e32 v135, v134
	v_mul_f32_e32 v142, v21, v142
	v_mul_f32_e32 v143, v20, v135
	v_cvt_pk_bf16_f32 v134, v140, v131
	v_mul_f32_e32 v131, 0xbfb8aa3b, v14
	v_exp_f32_e32 v140, v131
	v_mul_f32_e32 v131, 0xbfb8aa3b, v15
	v_cvt_pk_bf16_f32 v135, v136, v137
	v_cvt_pk_bf16_f32 v136, v144, v141
	v_exp_f32_e32 v141, v131
	v_cvt_pk_bf16_f32 v137, v143, v142
	global_store_dwordx4 v[138:139], v[134:137], off offset:256
	v_ashrrev_i32_e32 v131, 31, v130
	v_lshlrev_b64 v[130:131], 11, v[130:131]
	v_pk_add_f32 v[134:135], v[140:141], 1.0 op_sel_hi:[1,0]
	v_mul_f32_e32 v136, 0xbfb8aa3b, v10
	v_exp_f32_e32 v136, v136
	v_lshl_add_u64 v[130:131], s[64:65], 0, v[130:131]
	v_rcp_f32_e32 v137, v135
	s_nop 0
	v_mul_f32_e32 v138, v15, v137
	v_mul_f32_e32 v137, 0xbfb8aa3b, v11
	v_exp_f32_e32 v137, v137
	s_nop 0
	v_pk_add_f32 v[136:137], v[136:137], 1.0 op_sel_hi:[1,0]
	v_rcp_f32_e32 v135, v134
	v_rcp_f32_e32 v134, v137
	v_mul_f32_e32 v140, v14, v135
	v_mul_f32_e32 v142, v11, v134
	v_mul_f32_e32 v134, 0xbfb8aa3b, v16
	v_mul_f32_e32 v135, 0xbfb8aa3b, v17
	v_exp_f32_e32 v134, v134
	v_exp_f32_e32 v135, v135
	v_rcp_f32_e32 v137, v136
	v_pk_add_f32 v[134:135], v[134:135], 1.0 op_sel_hi:[1,0]
	v_mul_f32_e32 v143, v10, v137
	v_mul_f32_e32 v136, 0xbfb8aa3b, v12
	v_exp_f32_e32 v136, v136
	v_rcp_f32_e32 v137, v135
	s_nop 0
	v_mul_f32_e32 v135, v17, v137
	v_mul_f32_e32 v137, 0xbfb8aa3b, v13
	v_exp_f32_e32 v137, v137
	s_nop 0
	v_pk_add_f32 v[136:137], v[136:137], 1.0 op_sel_hi:[1,0]
	v_rcp_f32_e32 v139, v134
	s_nop 0
	v_mul_f32_e32 v139, v16, v139
	v_cvt_pk_bf16_f32 v135, v139, v135
	v_rcp_f32_e32 v134, v137
	v_mul_f32_e32 v139, 0xbfb8aa3b, v7
	v_mul_f32_e32 v137, v13, v134
	v_rcp_f32_e32 v134, v136
	s_nop 0
	v_mul_f32_e32 v141, v12, v134
	v_cvt_pk_bf16_f32 v134, v140, v138
	v_mul_f32_e32 v138, 0xbfb8aa3b, v6
	v_exp_f32_e32 v138, v138
	v_exp_f32_e32 v139, v139
	v_cvt_pk_bf16_f32 v137, v141, v137
	v_lshl_add_u64 v[140:141], v[130:131], 0, v[132:133]
	v_cvt_pk_bf16_f32 v136, v143, v142
	v_pk_add_f32 v[130:131], v[138:139], 1.0 op_sel_hi:[1,0]
	global_store_dwordx4 v[140:141], v[134:137], off
	v_mul_f32_e32 v132, 0xbfb8aa3b, v2
	v_exp_f32_e32 v132, v132
	v_rcp_f32_e32 v133, v131
	s_nop 0
	v_mul_f32_e32 v135, v7, v133
	v_mul_f32_e32 v133, 0xbfb8aa3b, v3
	v_exp_f32_e32 v133, v133
	s_nop 0
	v_pk_add_f32 v[132:133], v[132:133], 1.0 op_sel_hi:[1,0]
	v_rcp_f32_e32 v131, v130
	v_rcp_f32_e32 v130, v133
	v_mul_f32_e32 v136, v6, v131
	v_mul_f32_e32 v138, v3, v130
	v_mul_f32_e32 v130, 0xbfb8aa3b, v8
	v_mul_f32_e32 v131, 0xbfb8aa3b, v9
	v_exp_f32_e32 v130, v130
	v_exp_f32_e32 v131, v131
	v_rcp_f32_e32 v133, v132
	v_pk_add_f32 v[130:131], v[130:131], 1.0 op_sel_hi:[1,0]
	v_mul_f32_e32 v139, v2, v133
	v_mul_f32_e32 v132, 0xbfb8aa3b, v4
	v_exp_f32_e32 v132, v132
	v_rcp_f32_e32 v133, v131
	s_nop 0
	v_mul_f32_e32 v131, v9, v133
	v_mul_f32_e32 v133, 0xbfb8aa3b, v5
	v_exp_f32_e32 v133, v133
	s_nop 0
	v_pk_add_f32 v[132:133], v[132:133], 1.0 op_sel_hi:[1,0]
	v_rcp_f32_e32 v134, v130
	s_nop 0
	v_mul_f32_e32 v134, v8, v134
	v_cvt_pk_bf16_f32 v131, v134, v131
	v_rcp_f32_e32 v130, v133
	s_nop 0
	v_mul_f32_e32 v133, v5, v130
	s_mov_b64 s[14:15], 0
	v_rcp_f32_e32 v130, v132
	s_nop 0
	v_mul_f32_e32 v137, v4, v130
	v_cvt_pk_bf16_f32 v130, v136, v135
	v_cvt_pk_bf16_f32 v132, v139, v138
	v_cvt_pk_bf16_f32 v133, v137, v133
	global_store_dwordx4 v[140:141], v[130:133], off offset:256

.LBB0_1334:
	s_add_i32 s19, s19, 1
	s_cmp_lg_u32 s19, 17
	s_waitcnt lgkmcnt(0)
	s_barrier
	s_cbranch_scc0 .LBB0_1331
.LBB0_1335:
	s_and_b64 s[14:15], s[4:5], exec
	s_cselect_b32 s98, 0, 1
	s_sub_u32 s98, s19, s98
	s_cmp_gt_u32 s98, 15
	s_cbranch_scc1 .LBB0_1334
	s_lshr_b32 s28, s98, 1
	s_bitcmp0_b32 s98, 0
	s_mov_b64 s[14:15], -1
	s_cbranch_scc1 .LBB0_1341
	ds_read_b128 v[66:69], v146 offset:17152
	ds_read_b128 v[70:73], v146
	ds_read_b128 v[82:85], v146 offset:17184
	ds_read_b128 v[86:89], v146 offset:32
	s_sub_i32 s29, 7, s28
	s_and_b64 s[14:15], s[4:5], exec
	s_waitcnt lgkmcnt(2)
	v_mfma_f32_32x32x16_bf16 v[66:81], v[66:69], v[70:73], 0
	s_cselect_b32 s14, s28, s29
	s_cmp_gt_u32 s98, 7
	s_mov_b64 s[38:39], -1
	s_waitcnt lgkmcnt(0)
	v_mfma_f32_32x32x16_bf16 v[66:81], v[82:85], v[86:89], v[66:81]
	ds_read_b128 v[82:85], v146 offset:17216
	ds_read_b128 v[86:89], v146 offset:64
	ds_read_b128 v[90:93], v146 offset:17248
	ds_read_b128 v[94:97], v146 offset:96
	s_waitcnt lgkmcnt(2)
	v_mfma_f32_32x32x16_bf16 v[66:81], v[82:85], v[86:89], v[66:81]
	s_waitcnt lgkmcnt(0)
	v_mfma_f32_32x32x16_bf16 v[66:81], v[90:93], v[94:97], v[66:81]
	ds_read_b128 v[82:85], v146 offset:17280
	ds_read_b128 v[86:89], v146 offset:128
	ds_read_b128 v[90:93], v146 offset:17312
	ds_read_b128 v[94:97], v146 offset:160
	s_waitcnt lgkmcnt(2)
	v_mfma_f32_32x32x16_bf16 v[66:81], v[82:85], v[86:89], v[66:81]
	s_waitcnt lgkmcnt(0)
	v_mfma_f32_32x32x16_bf16 v[66:81], v[90:93], v[94:97], v[66:81]
	ds_read_b128 v[82:85], v146 offset:17344
	ds_read_b128 v[86:89], v146 offset:192
	ds_read_b128 v[90:93], v146 offset:17376
	ds_read_b128 v[94:97], v146 offset:224
	s_waitcnt lgkmcnt(2)
	v_mfma_f32_32x32x16_bf16 v[66:81], v[82:85], v[86:89], v[66:81]
	ds_read_b64_tr_b16 v[82:83], v202 offset:36096
	ds_read_b64_tr_b16 v[84:85], v202 offset:38656
	ds_read_b64_tr_b16 v[86:87], v202 offset:41216
	ds_read_b64_tr_b16 v[88:89], v202 offset:43776
	s_waitcnt lgkmcnt(4)
	v_mfma_f32_32x32x16_bf16 v[66:81], v[90:93], v[94:97], v[66:81]
	v_add_u32_e32 v94, 0x2000, v203
	s_nop 10
	v_cvt_pk_bf16_f32 v66, v66, v67
	v_cvt_pk_bf16_f32 v67, v68, v69
	v_cvt_pk_bf16_f32 v68, v70, v71
	v_cvt_pk_bf16_f32 v69, v72, v73
	v_and_b32_e32 v66, v178, v66
	v_and_b32_e32 v67, v179, v67
	v_and_b32_e32 v68, v180, v68
	v_and_b32_e32 v69, v181, v69
	v_cvt_pk_bf16_f32 v70, v74, v75
	v_cvt_pk_bf16_f32 v91, v76, v77
	v_cvt_pk_bf16_f32 v92, v78, v79
	v_cvt_pk_bf16_f32 v93, v80, v81
	v_and_b32_e32 v90, v182, v70
	s_waitcnt lgkmcnt(2)
	v_mfma_f32_32x32x16_bf16 v[66:81], v[66:69], v[82:85], 0
	v_and_b32_e32 v91, v191, v91
	v_and_b32_e32 v92, v194, v92
	v_and_b32_e32 v93, v195, v93
	ds_read2_b64 v[82:85], v94 offset0:64 offset1:66
	s_waitcnt lgkmcnt(1)
	v_mfma_f32_32x32x16_bf16 v[66:81], v[90:93], v[86:89], v[66:81]
	v_cvt_pk_bf16_f32 v86, v2, v3
	v_cvt_pk_bf16_f32 v87, v4, v5
	v_cvt_pk_bf16_f32 v88, v6, v7
	v_cvt_pk_bf16_f32 v89, v8, v9
	s_waitcnt lgkmcnt(0)
	s_nop 0
	v_mfma_f32_32x32x16_bf16 v[66:81], v[82:85], v[86:89], v[66:81]
	ds_read2_b64 v[82:85], v94 offset0:68 offset1:70
	v_cvt_pk_bf16_f32 v86, v10, v11
	v_cvt_pk_bf16_f32 v87, v12, v13
	v_cvt_pk_bf16_f32 v88, v14, v15
	v_cvt_pk_bf16_f32 v89, v16, v17
	s_waitcnt lgkmcnt(0)
	s_nop 0
	v_mfma_f32_32x32x16_bf16 v[66:81], v[82:85], v[86:89], v[66:81]
	ds_read2_b64 v[82:85], v94 offset0:72 offset1:74
	v_cvt_pk_bf16_f32 v86, v18, v19
	v_cvt_pk_bf16_f32 v87, v20, v21
	v_cvt_pk_bf16_f32 v88, v22, v23
	v_cvt_pk_bf16_f32 v89, v24, v25
	s_waitcnt lgkmcnt(0)
	s_nop 0
	v_mfma_f32_32x32x16_bf16 v[66:81], v[82:85], v[86:89], v[66:81]
	ds_read2_b64 v[82:85], v94 offset0:76 offset1:78
	v_cvt_pk_bf16_f32 v86, v26, v27
	v_cvt_pk_bf16_f32 v87, v28, v29
	v_cvt_pk_bf16_f32 v88, v30, v31
	v_cvt_pk_bf16_f32 v89, v32, v33
	s_waitcnt lgkmcnt(0)
	s_nop 0
	v_mfma_f32_32x32x16_bf16 v[66:81], v[82:85], v[86:89], v[66:81]
	ds_read2_b64 v[82:85], v94 offset0:80 offset1:82
	v_cvt_pk_bf16_f32 v86, v34, v35
	v_cvt_pk_bf16_f32 v87, v36, v37
	v_cvt_pk_bf16_f32 v88, v38, v39
	v_cvt_pk_bf16_f32 v89, v40, v41
	s_waitcnt lgkmcnt(0)
	s_nop 0
	v_mfma_f32_32x32x16_bf16 v[66:81], v[82:85], v[86:89], v[66:81]
	ds_read2_b64 v[82:85], v94 offset0:84 offset1:86
	v_cvt_pk_bf16_f32 v86, v42, v43
	v_cvt_pk_bf16_f32 v87, v44, v45
	v_cvt_pk_bf16_f32 v88, v46, v47
	v_cvt_pk_bf16_f32 v89, v48, v49
	s_waitcnt lgkmcnt(0)
	s_nop 0
	v_mfma_f32_32x32x16_bf16 v[66:81], v[82:85], v[86:89], v[66:81]
	ds_read2_b64 v[82:85], v94 offset0:88 offset1:90
	v_cvt_pk_bf16_f32 v86, v50, v51
	v_cvt_pk_bf16_f32 v87, v52, v53
	v_cvt_pk_bf16_f32 v88, v54, v55
	v_cvt_pk_bf16_f32 v89, v56, v57
	s_waitcnt lgkmcnt(0)
	s_nop 0
	v_mfma_f32_32x32x16_bf16 v[66:81], v[82:85], v[86:89], v[66:81]
	ds_read2_b64 v[82:85], v94 offset0:92 offset1:94
	v_cvt_pk_bf16_f32 v86, v58, v59
	v_cvt_pk_bf16_f32 v87, v60, v61
	v_cvt_pk_bf16_f32 v88, v62, v63
	v_cvt_pk_bf16_f32 v89, v64, v65
	s_waitcnt lgkmcnt(0)
	s_nop 0
	v_mfma_f32_32x32x16_bf16 v[66:81], v[82:85], v[86:89], v[66:81]
	s_cbranch_scc1 .LBB0_1338
	s_mov_b64 s[38:39], 0

.LBB0_1344:
	s_or_b64 exec, exec, s[14:15]
	s_cmp_gt_u32 s98, 13
	s_cbranch_scc1 .LBB0_1334
	s_lshl_b32 s28, s28, 5
	s_add_i32 s29, s28, 32
	s_sub_i32 s30, 0xc7, s28
	s_and_b64 s[14:15], s[4:5], exec
	s_cselect_b32 s14, s29, s30
	s_add_i32 s14, s14, s63
	s_ashr_i32 s15, s14, 31
	s_lshl_b64 s[14:15], s[14:15], 11
	s_or_b64 s[14:15], s[14:15], s[26:27]
	v_lshl_add_u64 v[66:67], v[154:155], 0, s[14:15]
	s_sub_i32 s30, 0xc6, s28
	s_add_i32 s31, s28, 33
	global_load_dword v183, v[66:67], off
	v_lshl_add_u64 v[66:67], v[156:157], 0, s[14:15]
	s_and_b64 s[14:15], s[4:5], exec
	s_cselect_b32 s14, s31, s30
	s_add_i32 s14, s14, s63
	s_ashr_i32 s15, s14, 31
	s_lshl_b64 s[14:15], s[14:15], 11
	s_or_b64 s[14:15], s[14:15], s[26:27]
	global_load_dword v184, v[66:67], off
	v_lshl_add_u64 v[66:67], v[154:155], 0, s[14:15]
	s_sub_i32 s30, 0xc5, s28
	s_add_i32 s31, s28, 34
	global_load_dword v185, v[66:67], off
	v_lshl_add_u64 v[66:67], v[156:157], 0, s[14:15]
	s_and_b64 s[14:15], s[4:5], exec
	s_cselect_b32 s14, s31, s30
	s_add_i32 s14, s14, s63
	s_ashr_i32 s15, s14, 31
	s_lshl_b64 s[14:15], s[14:15], 11
	s_or_b64 s[14:15], s[14:15], s[26:27]
	global_load_dword v186, v[66:67], off
	v_lshl_add_u64 v[66:67], v[154:155], 0, s[14:15]
	s_sub_i32 s30, 0xc4, s28
	s_add_i32 s31, s28, 35
	global_load_dword v187, v[66:67], off
	v_lshl_add_u64 v[66:67], v[156:157], 0, s[14:15]
	s_and_b64 s[14:15], s[4:5], exec
	s_cselect_b32 s14, s31, s30
	s_add_i32 s14, s14, s63
	s_ashr_i32 s15, s14, 31
	s_lshl_b64 s[14:15], s[14:15], 11
	s_or_b64 s[14:15], s[14:15], s[26:27]
	global_load_dword v188, v[66:67], off
	v_lshl_add_u64 v[66:67], v[154:155], 0, s[14:15]
	s_sub_i32 s30, 0xc3, s28
	s_add_i32 s31, s28, 36
	global_load_dword v189, v[66:67], off
	v_lshl_add_u64 v[66:67], v[156:157], 0, s[14:15]
	s_and_b64 s[14:15], s[4:5], exec
	s_cselect_b32 s14, s31, s30
	s_add_i32 s14, s14, s63
	s_ashr_i32 s15, s14, 31
	s_lshl_b64 s[14:15], s[14:15], 11
	s_or_b64 s[14:15], s[14:15], s[26:27]
	global_load_dword v190, v[66:67], off
	v_lshl_add_u64 v[66:67], v[154:155], 0, s[14:15]
	s_sub_i32 s30, 0xc2, s28
	s_add_i32 s31, s28, 37
	global_load_dword v192, v[66:67], off
	v_lshl_add_u64 v[66:67], v[156:157], 0, s[14:15]
	s_and_b64 s[14:15], s[4:5], exec
	s_cselect_b32 s14, s31, s30
	s_add_i32 s14, s14, s63
	s_ashr_i32 s15, s14, 31
	s_lshl_b64 s[14:15], s[14:15], 11
	s_or_b64 s[14:15], s[14:15], s[26:27]
	global_load_dword v193, v[66:67], off
	v_lshl_add_u64 v[66:67], v[154:155], 0, s[14:15]
	s_sub_i32 s30, 0xc1, s28
	s_add_i32 s31, s28, 38
	global_load_dword v197, v[66:67], off
	v_lshl_add_u64 v[66:67], v[156:157], 0, s[14:15]
	s_and_b64 s[14:15], s[4:5], exec
	s_cselect_b32 s14, s31, s30
	s_add_i32 s14, s14, s63
	s_ashr_i32 s15, s14, 31
	s_lshl_b64 s[14:15], s[14:15], 11
	s_or_b64 s[14:15], s[14:15], s[26:27]
	global_load_dword v198, v[66:67], off
	v_lshl_add_u64 v[66:67], v[154:155], 0, s[14:15]
	s_sub_i32 s30, 0xc0, s28
	s_add_i32 s28, s28, 39
	global_load_dword v200, v[66:67], off
	v_lshl_add_u64 v[66:67], v[156:157], 0, s[14:15]
	s_and_b64 s[14:15], s[4:5], exec
	s_cselect_b32 s14, s28, s30
	s_add_i32 s14, s14, s63
	s_ashr_i32 s15, s14, 31
	s_lshl_b64 s[14:15], s[14:15], 11
	s_or_b64 s[14:15], s[14:15], s[26:27]
	global_load_dword v201, v[66:67], off
	v_lshl_add_u64 v[66:67], v[154:155], 0, s[14:15]
	global_load_dword v214, v[66:67], off
	v_lshl_add_u64 v[66:67], v[156:157], 0, s[14:15]
	s_and_b64 s[14:15], s[4:5], exec
	s_cselect_b32 s14, s29, s30
	s_add_i32 s14, s14, s63
	s_ashr_i32 s15, s14, 31
	s_lshl_b64 s[14:15], s[14:15], 11
	global_load_dword v216, v[66:67], off
	v_lshl_add_u64 v[66:67], v[158:159], 0, s[14:15]
	global_load_dwordx4 v[130:133], v[66:67], off offset:16
	global_load_dwordx4 v[134:137], v[66:67], off
	s_branch .LBB0_1334

.LBB0_1622:
	s_lshl_b32 s14, s34, 8
	s_ashr_i32 s15, s14, 31
	s_lshl_b64 s[14:15], s[14:15], 13
	v_readlane_b32 s28, v249, 32
	v_readlane_b32 s29, v249, 33
	s_add_u32 s17, s28, s14
	s_addc_u32 s29, s29, s15
	s_lshl_b32 s14, s48, 8
	v_mov_b32_e32 v146, v1
	v_mov_b32_e32 v147, v148
	s_ashr_i32 s15, s14, 31
	s_lshl_b64 s[14:15], s[14:15], 1
	v_add_u32_e32 v146, s40, v146
	v_max_f32_e32 v126, 0, v126
	v_max_f32_e32 v122, 0, v122
	v_max_f32_e32 v127, 0, v127
	v_max_f32_e32 v123, 0, v123
	s_add_u32 s28, s17, s14
	v_lshl_add_u32 v154, v147, 3, s41
	v_ashrrev_i32_e32 v147, 31, v146
	v_pk_mul_f32 v[126:127], v[126:127], v[126:127]
	v_pk_mul_f32 v[122:123], v[122:123], v[122:123]
	v_max_f32_e32 v128, 0, v128
	v_max_f32_e32 v124, 0, v124
	v_max_f32_e32 v129, 0, v129
	v_max_f32_e32 v125, 0, v125
	s_addc_u32 s29, s29, s15
	v_pk_mul_f32 v[128:129], v[128:129], v[128:129]
	v_pk_mul_f32 v[156:157], v[124:125], v[124:125]
	v_cvt_pk_bf16_f32 v124, v126, v127
	v_cvt_pk_bf16_f32 v126, v122, v123
	v_lshlrev_b64 v[122:123], 13, v[146:147]
	v_ashrrev_i32_e32 v155, 31, v154
	v_cvt_pk_bf16_f32 v125, v128, v129
	v_lshl_add_u64 v[128:129], s[28:29], 0, v[122:123]
	v_lshlrev_b64 v[122:123], 1, v[154:155]
	v_cvt_pk_bf16_f32 v127, v156, v157
	v_lshl_add_u64 v[128:129], v[128:129], 0, v[122:123]
	v_max_f32_e32 v114, 0, v114
	v_max_f32_e32 v115, 0, v115
	global_store_dwordx4 v[128:129], v[124:127], off
	s_nop 1
	v_pk_mul_f32 v[124:125], v[114:115], v[114:115]
	v_max_f32_e32 v116, 0, v116
	v_max_f32_e32 v118, 0, v118
	v_max_f32_e32 v119, 0, v119
	v_max_f32_e32 v114, 0, v120
	v_max_f32_e32 v115, 0, v121
	v_max_f32_e32 v117, 0, v117
	v_pk_mul_f32 v[118:119], v[118:119], v[118:119]
	v_pk_mul_f32 v[120:121], v[114:115], v[114:115]
	v_pk_mul_f32 v[126:127], v[116:117], v[116:117]
	v_cvt_pk_bf16_f32 v114, v118, v119
	v_cvt_pk_bf16_f32 v115, v120, v121
	v_cvt_pk_bf16_f32 v116, v124, v125
	v_cvt_pk_bf16_f32 v117, v126, v127
	v_max_f32_e32 v106, 0, v106
	v_max_f32_e32 v107, 0, v107
	global_store_dwordx4 v[128:129], v[114:117], off offset:256
	s_nop 1
	v_pk_mul_f32 v[116:117], v[106:107], v[106:107]
	v_add_u32_e32 v114, 16, v146
	v_max_f32_e32 v110, 0, v110
	v_max_f32_e32 v111, 0, v111
	v_max_f32_e32 v108, 0, v108
	v_ashrrev_i32_e32 v115, 31, v114
	v_pk_mul_f32 v[110:111], v[110:111], v[110:111]
	v_max_f32_e32 v106, 0, v112
	v_max_f32_e32 v107, 0, v113
	v_max_f32_e32 v109, 0, v109
	v_pk_mul_f32 v[112:113], v[106:107], v[106:107]
	v_cvt_pk_bf16_f32 v106, v110, v111
	v_lshlrev_b64 v[110:111], 13, v[114:115]
	v_pk_mul_f32 v[118:119], v[108:109], v[108:109]
	v_lshl_add_u64 v[110:111], s[28:29], 0, v[110:111]
	v_cvt_pk_bf16_f32 v107, v112, v113
	v_cvt_pk_bf16_f32 v108, v116, v117
	v_cvt_pk_bf16_f32 v109, v118, v119
	v_lshl_add_u64 v[110:111], v[110:111], 0, v[122:123]
	v_max_f32_e32 v98, 0, v98
	v_max_f32_e32 v99, 0, v99
	global_store_dwordx4 v[110:111], v[106:109], off
	s_nop 1
	v_pk_mul_f32 v[106:107], v[98:99], v[98:99]
	v_max_f32_e32 v100, 0, v100
	v_max_f32_e32 v102, 0, v102
	v_max_f32_e32 v103, 0, v103
	v_max_f32_e32 v98, 0, v104
	v_max_f32_e32 v99, 0, v105
	v_max_f32_e32 v101, 0, v101
	v_pk_mul_f32 v[102:103], v[102:103], v[102:103]
	v_pk_mul_f32 v[104:105], v[98:99], v[98:99]
	v_pk_mul_f32 v[108:109], v[100:101], v[100:101]
	v_cvt_pk_bf16_f32 v98, v102, v103
	v_cvt_pk_bf16_f32 v99, v104, v105
	v_cvt_pk_bf16_f32 v100, v106, v107
	v_cvt_pk_bf16_f32 v101, v108, v109
	v_max_f32_e32 v90, 0, v90
	v_max_f32_e32 v91, 0, v91
	global_store_dwordx4 v[110:111], v[98:101], off offset:256
	s_nop 1
	v_pk_mul_f32 v[100:101], v[90:91], v[90:91]
	v_add_u32_e32 v98, 32, v146
	v_max_f32_e32 v94, 0, v94
	v_max_f32_e32 v95, 0, v95
	v_max_f32_e32 v92, 0, v92
	v_ashrrev_i32_e32 v99, 31, v98
	v_pk_mul_f32 v[94:95], v[94:95], v[94:95]
	v_max_f32_e32 v90, 0, v96
	v_max_f32_e32 v91, 0, v97
	v_max_f32_e32 v93, 0, v93
	v_pk_mul_f32 v[96:97], v[90:91], v[90:91]
	v_cvt_pk_bf16_f32 v90, v94, v95
	v_lshlrev_b64 v[94:95], 13, v[98:99]
	v_pk_mul_f32 v[102:103], v[92:93], v[92:93]
	v_lshl_add_u64 v[94:95], s[28:29], 0, v[94:95]
	v_cvt_pk_bf16_f32 v91, v96, v97
	v_cvt_pk_bf16_f32 v92, v100, v101
	v_cvt_pk_bf16_f32 v93, v102, v103
	v_lshl_add_u64 v[94:95], v[94:95], 0, v[122:123]
	v_max_f32_e32 v82, 0, v82
	v_max_f32_e32 v83, 0, v83
	global_store_dwordx4 v[94:95], v[90:93], off
	s_nop 1
	v_pk_mul_f32 v[90:91], v[82:83], v[82:83]
	v_max_f32_e32 v84, 0, v84
	v_max_f32_e32 v86, 0, v86
	v_max_f32_e32 v87, 0, v87
	v_max_f32_e32 v82, 0, v88
	v_max_f32_e32 v83, 0, v89
	v_max_f32_e32 v85, 0, v85
	v_pk_mul_f32 v[86:87], v[86:87], v[86:87]
	v_pk_mul_f32 v[88:89], v[82:83], v[82:83]
	v_pk_mul_f32 v[92:93], v[84:85], v[84:85]
	v_cvt_pk_bf16_f32 v82, v86, v87
	v_cvt_pk_bf16_f32 v83, v88, v89
	v_cvt_pk_bf16_f32 v84, v90, v91
	v_cvt_pk_bf16_f32 v85, v92, v93
	v_max_f32_e32 v74, 0, v74
	v_max_f32_e32 v75, 0, v75
	global_store_dwordx4 v[94:95], v[82:85], off offset:256
	s_nop 1
	v_pk_mul_f32 v[84:85], v[74:75], v[74:75]
	v_add_u32_e32 v82, 48, v146
	v_max_f32_e32 v78, 0, v78
	v_max_f32_e32 v79, 0, v79
	v_max_f32_e32 v76, 0, v76
	v_ashrrev_i32_e32 v83, 31, v82
	v_pk_mul_f32 v[78:79], v[78:79], v[78:79]
	v_max_f32_e32 v74, 0, v80
	v_max_f32_e32 v75, 0, v81
	v_max_f32_e32 v77, 0, v77
	v_pk_mul_f32 v[80:81], v[74:75], v[74:75]
	v_cvt_pk_bf16_f32 v74, v78, v79
	v_lshlrev_b64 v[78:79], 13, v[82:83]
	v_pk_mul_f32 v[86:87], v[76:77], v[76:77]
	v_lshl_add_u64 v[78:79], s[28:29], 0, v[78:79]
	v_cvt_pk_bf16_f32 v75, v80, v81
	v_cvt_pk_bf16_f32 v76, v84, v85
	v_cvt_pk_bf16_f32 v77, v86, v87
	v_lshl_add_u64 v[78:79], v[78:79], 0, v[122:123]
	v_max_f32_e32 v66, 0, v66
	v_max_f32_e32 v67, 0, v67
	global_store_dwordx4 v[78:79], v[74:77], off
	s_nop 1
	v_pk_mul_f32 v[74:75], v[66:67], v[66:67]
	v_max_f32_e32 v68, 0, v68
	v_max_f32_e32 v70, 0, v70
	v_max_f32_e32 v71, 0, v71
	v_max_f32_e32 v66, 0, v72
	v_max_f32_e32 v67, 0, v73
	v_max_f32_e32 v69, 0, v69
	v_pk_mul_f32 v[70:71], v[70:71], v[70:71]
	v_pk_mul_f32 v[72:73], v[66:67], v[66:67]
	v_pk_mul_f32 v[76:77], v[68:69], v[68:69]
	v_cvt_pk_bf16_f32 v66, v70, v71
	v_cvt_pk_bf16_f32 v67, v72, v73
	v_cvt_pk_bf16_f32 v68, v74, v75
	v_cvt_pk_bf16_f32 v69, v76, v77
	v_max_f32_e32 v58, 0, v58
	v_max_f32_e32 v59, 0, v59
	global_store_dwordx4 v[78:79], v[66:69], off offset:256
	s_nop 1
	v_pk_mul_f32 v[68:69], v[58:59], v[58:59]
	v_add_u32_e32 v66, 0x80, v146
	v_max_f32_e32 v62, 0, v62
	v_max_f32_e32 v63, 0, v63
	v_max_f32_e32 v60, 0, v60
	v_ashrrev_i32_e32 v67, 31, v66
	v_pk_mul_f32 v[62:63], v[62:63], v[62:63]
	v_max_f32_e32 v58, 0, v64
	v_max_f32_e32 v59, 0, v65
	v_max_f32_e32 v61, 0, v61
	v_pk_mul_f32 v[64:65], v[58:59], v[58:59]
	v_cvt_pk_bf16_f32 v58, v62, v63
	v_lshlrev_b64 v[62:63], 13, v[66:67]
	v_pk_mul_f32 v[70:71], v[60:61], v[60:61]
	v_lshl_add_u64 v[62:63], s[28:29], 0, v[62:63]
	v_cvt_pk_bf16_f32 v59, v64, v65
	v_cvt_pk_bf16_f32 v60, v68, v69
	v_cvt_pk_bf16_f32 v61, v70, v71
	v_lshl_add_u64 v[62:63], v[62:63], 0, v[122:123]
	v_max_f32_e32 v50, 0, v50
	v_max_f32_e32 v51, 0, v51
	global_store_dwordx4 v[62:63], v[58:61], off
	s_nop 1
	v_pk_mul_f32 v[58:59], v[50:51], v[50:51]
	v_max_f32_e32 v52, 0, v52
	v_max_f32_e32 v54, 0, v54
	v_max_f32_e32 v55, 0, v55
	v_max_f32_e32 v50, 0, v56
	v_max_f32_e32 v51, 0, v57
	v_max_f32_e32 v53, 0, v53
	v_pk_mul_f32 v[54:55], v[54:55], v[54:55]
	v_pk_mul_f32 v[56:57], v[50:51], v[50:51]
	v_pk_mul_f32 v[60:61], v[52:53], v[52:53]
	v_cvt_pk_bf16_f32 v50, v54, v55
	v_cvt_pk_bf16_f32 v51, v56, v57
	v_cvt_pk_bf16_f32 v52, v58, v59
	v_cvt_pk_bf16_f32 v53, v60, v61
	v_max_f32_e32 v42, 0, v42
	v_max_f32_e32 v43, 0, v43
	global_store_dwordx4 v[62:63], v[50:53], off offset:256
	s_nop 1
	v_pk_mul_f32 v[52:53], v[42:43], v[42:43]
	v_add_u32_e32 v50, 0x90, v146
	v_max_f32_e32 v46, 0, v46
	v_max_f32_e32 v47, 0, v47
	v_max_f32_e32 v44, 0, v44
	v_ashrrev_i32_e32 v51, 31, v50
	v_pk_mul_f32 v[46:47], v[46:47], v[46:47]
	v_max_f32_e32 v42, 0, v48
	v_max_f32_e32 v43, 0, v49
	v_max_f32_e32 v45, 0, v45
	v_pk_mul_f32 v[48:49], v[42:43], v[42:43]
	v_cvt_pk_bf16_f32 v42, v46, v47
	v_lshlrev_b64 v[46:47], 13, v[50:51]
	v_pk_mul_f32 v[54:55], v[44:45], v[44:45]
	v_lshl_add_u64 v[46:47], s[28:29], 0, v[46:47]
	v_cvt_pk_bf16_f32 v43, v48, v49
	v_cvt_pk_bf16_f32 v44, v52, v53
	v_cvt_pk_bf16_f32 v45, v54, v55
	v_lshl_add_u64 v[46:47], v[46:47], 0, v[122:123]
	v_max_f32_e32 v34, 0, v34
	v_max_f32_e32 v35, 0, v35
	global_store_dwordx4 v[46:47], v[42:45], off
	s_nop 1
	v_pk_mul_f32 v[42:43], v[34:35], v[34:35]
	v_max_f32_e32 v36, 0, v36
	v_max_f32_e32 v38, 0, v38
	v_max_f32_e32 v39, 0, v39
	v_max_f32_e32 v34, 0, v40
	v_max_f32_e32 v35, 0, v41
	v_max_f32_e32 v37, 0, v37
	v_pk_mul_f32 v[38:39], v[38:39], v[38:39]
	v_pk_mul_f32 v[40:41], v[34:35], v[34:35]
	v_pk_mul_f32 v[44:45], v[36:37], v[36:37]
	v_cvt_pk_bf16_f32 v34, v38, v39
	v_cvt_pk_bf16_f32 v35, v40, v41
	v_cvt_pk_bf16_f32 v36, v42, v43
	v_cvt_pk_bf16_f32 v37, v44, v45
	v_max_f32_e32 v26, 0, v26
	v_max_f32_e32 v27, 0, v27
	global_store_dwordx4 v[46:47], v[34:37], off offset:256
	s_nop 1
	v_pk_mul_f32 v[36:37], v[26:27], v[26:27]
	v_add_u32_e32 v34, 0xa0, v146
	v_max_f32_e32 v30, 0, v30
	v_max_f32_e32 v31, 0, v31
	v_max_f32_e32 v28, 0, v28
	v_ashrrev_i32_e32 v35, 31, v34
	v_pk_mul_f32 v[30:31], v[30:31], v[30:31]
	v_max_f32_e32 v26, 0, v32
	v_max_f32_e32 v27, 0, v33
	v_max_f32_e32 v29, 0, v29
	v_pk_mul_f32 v[32:33], v[26:27], v[26:27]
	v_cvt_pk_bf16_f32 v26, v30, v31
	v_lshlrev_b64 v[30:31], 13, v[34:35]
	v_pk_mul_f32 v[38:39], v[28:29], v[28:29]
	v_lshl_add_u64 v[30:31], s[28:29], 0, v[30:31]
	v_cvt_pk_bf16_f32 v27, v32, v33
	v_cvt_pk_bf16_f32 v28, v36, v37
	v_cvt_pk_bf16_f32 v29, v38, v39
	v_lshl_add_u64 v[30:31], v[30:31], 0, v[122:123]
	v_max_f32_e32 v18, 0, v18
	v_max_f32_e32 v19, 0, v19
	global_store_dwordx4 v[30:31], v[26:29], off
	s_nop 1
	v_pk_mul_f32 v[26:27], v[18:19], v[18:19]
	v_max_f32_e32 v20, 0, v20
	v_max_f32_e32 v22, 0, v22
	v_max_f32_e32 v23, 0, v23
	v_max_f32_e32 v18, 0, v24
	v_max_f32_e32 v19, 0, v25
	v_max_f32_e32 v21, 0, v21
	v_pk_mul_f32 v[22:23], v[22:23], v[22:23]
	v_pk_mul_f32 v[24:25], v[18:19], v[18:19]
	v_pk_mul_f32 v[28:29], v[20:21], v[20:21]
	v_cvt_pk_bf16_f32 v18, v22, v23
	v_cvt_pk_bf16_f32 v19, v24, v25
	v_cvt_pk_bf16_f32 v20, v26, v27
	v_cvt_pk_bf16_f32 v21, v28, v29
	v_max_f32_e32 v10, 0, v10
	v_max_f32_e32 v11, 0, v11
	global_store_dwordx4 v[30:31], v[18:21], off offset:256
	s_nop 1
	v_pk_mul_f32 v[20:21], v[10:11], v[10:11]
	v_add_u32_e32 v18, 0xb0, v146
	v_max_f32_e32 v14, 0, v14
	v_max_f32_e32 v15, 0, v15
	v_max_f32_e32 v12, 0, v12
	v_ashrrev_i32_e32 v19, 31, v18
	v_pk_mul_f32 v[14:15], v[14:15], v[14:15]
	v_max_f32_e32 v10, 0, v16
	v_max_f32_e32 v11, 0, v17
	v_max_f32_e32 v13, 0, v13
	v_pk_mul_f32 v[16:17], v[10:11], v[10:11]
	v_cvt_pk_bf16_f32 v10, v14, v15
	v_lshlrev_b64 v[14:15], 13, v[18:19]
	v_pk_mul_f32 v[22:23], v[12:13], v[12:13]
	v_lshl_add_u64 v[14:15], s[28:29], 0, v[14:15]
	v_cvt_pk_bf16_f32 v11, v16, v17
	v_cvt_pk_bf16_f32 v12, v20, v21
	v_cvt_pk_bf16_f32 v13, v22, v23
	v_lshl_add_u64 v[14:15], v[14:15], 0, v[122:123]
	v_max_f32_e32 v2, 0, v2
	v_max_f32_e32 v3, 0, v3
	global_store_dwordx4 v[14:15], v[10:13], off
	s_nop 1
	v_pk_mul_f32 v[10:11], v[2:3], v[2:3]
	v_max_f32_e32 v4, 0, v4
	v_max_f32_e32 v6, 0, v6
	v_max_f32_e32 v7, 0, v7
	v_max_f32_e32 v2, 0, v8
	v_max_f32_e32 v3, 0, v9
	v_max_f32_e32 v5, 0, v5
	v_pk_mul_f32 v[6:7], v[6:7], v[6:7]
	v_pk_mul_f32 v[8:9], v[2:3], v[2:3]
	v_pk_mul_f32 v[12:13], v[4:5], v[4:5]
	v_cvt_pk_bf16_f32 v2, v6, v7
	v_cvt_pk_bf16_f32 v3, v8, v9
	v_cvt_pk_bf16_f32 v4, v10, v11
	v_cvt_pk_bf16_f32 v5, v12, v13
	s_andn2_b64 vcc, exec, s[4:5]
	s_mov_b64 s[4:5], -1
	global_store_dwordx4 v[14:15], v[2:5], off offset:256
	s_cbranch_vccnz .LBB0_1615
	s_andn2_b64 vcc, exec, s[6:7]
	s_cbranch_vccnz .LBB0_1614
	s_barrier
	s_branch .LBB0_1614

	.amdhsa_kernel _ZN2fk3fwdENS_4ArgsE
		.amdhsa_group_segment_fixed_size 0
		.amdhsa_private_segment_fixed_size 0
		.amdhsa_kernarg_size 416
		.amdhsa_user_sgpr_count 2
		.amdhsa_user_sgpr_dispatch_ptr 0
		.amdhsa_user_sgpr_queue_ptr 0
		.amdhsa_user_sgpr_kernarg_segment_ptr 1
		.amdhsa_user_sgpr_dispatch_id 0
		.amdhsa_user_sgpr_kernarg_preload_length 0
		.amdhsa_user_sgpr_kernarg_preload_offset 0
		.amdhsa_user_sgpr_private_segment_size 0
		.amdhsa_uses_dynamic_stack 0
		.amdhsa_enable_private_segment 0
		.amdhsa_system_sgpr_workgroup_id_x 1
		.amdhsa_system_sgpr_workgroup_id_y 0
		.amdhsa_system_sgpr_workgroup_id_z 0
		.amdhsa_system_sgpr_workgroup_info 0
		.amdhsa_system_vgpr_workitem_id 0
		.amdhsa_next_free_vgpr 250
		.amdhsa_next_free_sgpr 102
		.amdhsa_accum_offset 252
		.amdhsa_reserve_vcc 1
		.amdhsa_float_round_mode_32 0
		.amdhsa_float_round_mode_16_64 0
		.amdhsa_float_denorm_mode_32 3
		.amdhsa_float_denorm_mode_16_64 3
		.amdhsa_dx10_clamp 1
		.amdhsa_ieee_mode 1
		.amdhsa_fp16_overflow 0
		.amdhsa_tg_split 0
		.amdhsa_exception_fp_ieee_invalid_op 0
		.amdhsa_exception_fp_denorm_src 0
		.amdhsa_exception_fp_ieee_div_zero 0
		.amdhsa_exception_fp_ieee_overflow 0
		.amdhsa_exception_fp_ieee_underflow 0
		.amdhsa_exception_fp_ieee_inexact 0
		.amdhsa_exception_int_div_zero 0
	.end_amdhsa_kernel

amdhsa.kernels:
  - .agpr_count:     0
    .args:
      - .offset:         0
        .size:           160
        .value_kind:     by_value
      - .offset:         160
        .size:           4
        .value_kind:     hidden_block_count_x
      - .offset:         164
        .size:           4
        .value_kind:     hidden_block_count_y
      - .offset:         168
        .size:           4
        .value_kind:     hidden_block_count_z
      - .offset:         172
        .size:           2
        .value_kind:     hidden_group_size_x
      - .offset:         174
        .size:           2
        .value_kind:     hidden_group_size_y
      - .offset:         176
        .size:           2
        .value_kind:     hidden_group_size_z
      - .offset:         178
        .size:           2
        .value_kind:     hidden_remainder_x
      - .offset:         180
        .size:           2
        .value_kind:     hidden_remainder_y
      - .offset:         182
        .size:           2
        .value_kind:     hidden_remainder_z
      - .offset:         200
        .size:           8
        .value_kind:     hidden_global_offset_x
      - .offset:         208
        .size:           8
        .value_kind:     hidden_global_offset_y
      - .offset:         216
        .size:           8
        .value_kind:     hidden_global_offset_z
      - .offset:         224
        .size:           2
        .value_kind:     hidden_grid_dims
      - .offset:         280
        .size:           4
        .value_kind:     hidden_dynamic_lds_size
    .group_segment_fixed_size: 0
    .kernarg_segment_align: 8
    .kernarg_segment_size: 416
    .language:       OpenCL C
    .language_version:
      - 2
      - 0
    .max_flat_workgroup_size: 512
    .name:           _ZN2fk3fwdENS_4ArgsE
    .private_segment_fixed_size: 0
    .sgpr_count:     108
    .sgpr_spill_count: 77
    .symbol:         _ZN2fk3fwdENS_4ArgsE.kd
    .uniform_work_group_size: 1
    .uses_dynamic_stack: false
    .vgpr_count:     250
    .vgpr_spill_count: 0
    .wavefront_size: 64
